# strategy 4 whole-kernel form: one static s_setprio 1 for waves 0-3 at kernel entry, every per-phase flip in the GEMM loops deleted
# baseline (speedup 1.0000x reference)
; #define LAS __attribute__((address_space(3)))
; #define IDS() int tid__ = threadIdx.x; asm volatile("" : "+v"(tid__)); const int lane = tid__ & 63, wave = __builtin_amdgcn_readfirstlane(tid__ >> 6), gw = blockIdx.x * 8 + wave, gwT = wave * G + blockIdx.x; (void)lane; (void)gw; (void)gwT
; __global__ void __launch_bounds__(512, 2) fwd(Args a) {
;     extern __shared__ __attribute__((aligned(16))) unsigned char lds_raw[];
;     LAS unsigned char* lds = (LAS unsigned char*)lds_raw;
;     const int G = gridDim.x, NGW = G * 8;
;     ...
;     unsigned char* ws = a.ws;
;     u64* ss = (u64*)(ws + WS_SS);
;     bf16_t* hb = (bf16_t*)(ws + WS_HB); bf16_t* ob = (bf16_t*)(ws + WS_OB); bf16_t* act = (bf16_t*)(ws + WS_R1); bf16_t* qkv = (bf16_t*)(ws + WS_R1);
;     const int lo = a.ph_lo, hi = a.ph_hi;
;     ...
;     volatile LAS unsigned* bst = (volatile LAS unsigned*)(lds + LDS_BYTES - 64);
;     if (threadIdx.x < 2) bst[threadIdx.x] = 0u;
;     XcdBarrier xbar; xbar.bar = (unsigned*)(ws + WS_BAR); xbar.x = 0; xbar.st = bst;
;     ...
;     if (IN(0)) { IDS(); prologue(a, lds, gw, NGW, wave, lane); __syncthreads(); }
_Z3fwd4Args:
	s_load_dwordx16 s[36:51], s[0:1], 0x0
	s_load_dwordx16 s[4:19], s[0:1], 0x40
	v_and_b32_e32 v236, 0x3ff, v0
	s_mov_b32 s60, s2
	v_cmp_gt_u32_e32 vcc, 2, v236
	s_waitcnt lgkmcnt(0)
	v_readfirstlane_b32 s100, v236
	s_lshr_b32 s100, s100, 6
	s_cmp_ge_u32 s100, 4
	s_cbranch_scc1 .Lglob_prio_skip
	s_setprio 1
.Lglob_prio_skip:
	v_writelane_b32 v252, s4, 0
	s_nop 1
	v_writelane_b32 v252, s5, 1
	v_writelane_b32 v252, s6, 2
	v_writelane_b32 v252, s7, 3
	v_writelane_b32 v252, s8, 4
	v_writelane_b32 v252, s9, 5
	v_writelane_b32 v252, s10, 6
	v_writelane_b32 v252, s11, 7
	v_writelane_b32 v252, s12, 8
	v_writelane_b32 v252, s13, 9
	v_writelane_b32 v252, s14, 10
	v_writelane_b32 v252, s15, 11
	v_writelane_b32 v252, s16, 12
	v_writelane_b32 v252, s17, 13
	v_writelane_b32 v252, s18, 14
	v_writelane_b32 v252, s19, 15
	s_load_dwordx8 s[8:15], s[0:1], 0x80
	s_load_dword s3, s[0:1], 0xa0
	s_add_u32 s0, s0, 0xa0
	s_addc_u32 s1, s1, 0
	v_writelane_b32 v252, s0, 16
	s_nop 1
	v_writelane_b32 v252, s1, 17
	s_and_saveexec_b64 s[0:1], vcc
	v_lshl_add_u32 v1, v236, 2, 0
	v_add_u32_e32 v1, 0x23fc0, v1
	v_mov_b32_e32 v2, 0
	ds_write_b32 v1, v2
	s_or_b64 exec, exec, s[0:1]
	s_waitcnt lgkmcnt(0)
	s_add_u32 s62, s12, 0x1ce00000
	s_addc_u32 s63, s13, 0
	s_mov_b64 s[18:19], s[14:15]
	s_mov_b64 s[16:17], s[12:13]
	s_mov_b64 s[14:15], s[10:11]
	s_mov_b64 s[12:13], s[8:9]
	s_add_u32 s8, s16, 0x7a400
	s_addc_u32 s9, s17, 0
	s_cmp_lt_i32 s18, 1
	v_writelane_b32 v252, s12, 18
	s_cselect_b64 s[0:1], -1, 0
	s_cmp_gt_i32 s19, 0
	v_writelane_b32 v252, s13, 19
	v_writelane_b32 v252, s14, 20
	v_writelane_b32 v252, s15, 21
	v_writelane_b32 v252, s16, 22
	v_writelane_b32 v252, s17, 23
	v_writelane_b32 v252, s18, 24
	v_writelane_b32 v252, s19, 25
	v_writelane_b32 v252, s36, 26
	s_cselect_b64 s[4:5], -1, 0
	s_and_b64 s[0:1], s[0:1], s[4:5]
	v_writelane_b32 v252, s37, 27
	v_writelane_b32 v252, s38, 28
	v_writelane_b32 v252, s39, 29
	v_writelane_b32 v252, s40, 30
	v_writelane_b32 v252, s41, 31
	v_writelane_b32 v252, s42, 32
	v_writelane_b32 v252, s43, 33
	v_writelane_b32 v252, s44, 34
	v_writelane_b32 v252, s45, 35
	v_writelane_b32 v252, s46, 36
	v_writelane_b32 v252, s47, 37
	v_writelane_b32 v252, s48, 38
	v_writelane_b32 v252, s49, 39
	v_writelane_b32 v252, s50, 40
	s_mov_b32 s2, 0
	s_and_b64 vcc, exec, s[0:1]
	v_writelane_b32 v252, s51, 41
	s_cbranch_vccnz .LBB0_4
	s_lshl_b32 s0, s60, 3
	v_writelane_b32 v252, s0, 42
	s_lshl_b32 s42, s3, 3
	s_cbranch_execz .LBB0_5
	s_branch .LBB0_152

; #define PG8_STAGE(bufoff, gbase, voff) do { _Pragma("unroll") for (int _i = 0; _i < 2; ++_i) \
;         __builtin_amdgcn_global_load_lds((const unsigned*)((const char*)(gbase) + (voff)[_i]), (LAS unsigned*)(lds + (bufoff) + ldsw + _i * 8192), 16, 0, 0); } while (0)
; #define PG8_LDA(dst, b, h) do { _Pragma("unroll") for (int m = 0; m < 4; ++m) _Pragma("unroll") for (int k = 0; k < 2; ++k) dst[m][k] = *(const LAS bf16x8*)(lds + PG8_SA(b, h) + aoff + m * 2048 + k * 1024); } while (0)
; #define PG8_LDB(dst, b, h) do { _Pragma("unroll") for (int n = 0; n < 2; ++n) _Pragma("unroll") for (int k = 0; k < 2; ++k) dst[n][k] = *(const LAS bf16x8*)(lds + PG8_SB(b, h) + boff + n * 2048 + k * 1024); } while (0)
; #define PG8_MMA(ai, bj, At, Bt) do { __builtin_amdgcn_s_setprio(1); _Pragma("unroll") for (int m = 0; m < 4; ++m) _Pragma("unroll") for (int n = 0; n < 2; ++n) _Pragma("unroll") for (int k = 0; k < 2; ++k) \
;         acc[ai][bj][m][n] = __builtin_amdgcn_mfma_f32_16x16x32_bf16(Bt[n][k], At[m][k], acc[ai][bj][m][n], 0, 0, 0); __builtin_amdgcn_s_setprio(0); } while (0)
; #define PG8_WAIT_V(n) asm volatile("s_waitcnt vmcnt(" #n ")" ::: "memory")
; #define PG8_WAIT_L(n) asm volatile("s_waitcnt lgkmcnt(" #n ")" ::: "memory")
; template <class Epi, class Sched, bool ALIGN_EPI = false, bool SP2 = false>
; __device__ __forceinline__ void gemm_phase(LAS unsigned char* lds, const Gemm g, const Sched& S, const Epi& E) {
;     ...
;         for (int t = 0; t < nt; t += 2) {
;             const bool last = (t == nt - 2);
;             const char* a1 = cA + (size_t)(t + 1) * kstep;
;             const char* a2 = last ? nA : cA + (size_t)(t + 2) * kstep; const char* b2 = last ? nB : cB + (size_t)(t + 2) * kstep;
;             const char* a3 = a2 + kstep; const char* b3 = b2 + kstep;
;             if (last && has_next) S.a_ready(nxt);
;             if constexpr (SP2) {
;             PG8_LDB(B0, 0, 0); PG8_LDB(B1, 0, 1); PG8_SCHED; PG8_LDA(At, 0, 0); PG8_STAGE(PG8_SA(1, 1), a1 + hstep, voffA);
;             PG8_WAIT_V(8); PG8_WAIT_L(0); PG8_BAR; PG8_MMA(0, 0, At, B0); PG8_MMA(0, 1, At, B1); PG8_BAR; PG8_SCHED;
;             PG8_LDA(At, 0, 1); PG8_STAGE(PG8_SB(0, 0), b2, voffB); PG8_STAGE(PG8_SB(0, 1), b2 + hstep, voffB); PG8_STAGE(PG8_SA(0, 0), a2, voffA);
;             PG8_WAIT_V(8); PG8_WAIT_L(0); PG8_BAR; PG8_MMA(1, 0, At, B0); PG8_MMA(1, 1, At, B1); PG8_BAR; PG8_SCHED;
.LBB0_173:
	s_add_u32 s26, s24, 0xfff80080
	s_addc_u32 s27, s25, -1
	s_add_i32 s45, 0, 0x10000
	s_cmp_eq_u32 s44, 28
	s_cselect_b32 s29, s7, s27
	s_cselect_b32 s28, s8, s26
	v_add_u32_e32 v140, s45, v145
	s_cselect_b32 s27, s17, s43
	s_cselect_b32 s26, s19, s35
	s_add_i32 s47, 0, 0x14000
	ds_read_b128 v[150:153], v140
	ds_read_b128 v[154:157], v140 offset:1024
	ds_read_b128 v[158:161], v140 offset:2048
	ds_read_b128 v[162:165], v140 offset:3072
	v_add_u32_e32 v140, s47, v145
	ds_read_b128 v[166:169], v140
	ds_read_b128 v[170:173], v140 offset:1024
	ds_read_b128 v[174:177], v140 offset:2048
	ds_read_b128 v[178:181], v140 offset:3072
	v_lshl_add_u64 v[140:141], s[24:25], 0, v[136:137]
	s_add_i32 m0, s30, 0xc000
	ds_read_b128 v[182:185], v149
	ds_read_b128 v[194:197], v149 offset:1024
	ds_read_b128 v[198:201], v149 offset:2048
	ds_read_b128 v[202:205], v149 offset:3072
	ds_read_b128 v[206:209], v149 offset:4096
	ds_read_b128 v[210:213], v149 offset:5120
	ds_read_b128 v[214:217], v149 offset:6144
	ds_read_b128 v[218:221], v149 offset:7168
	global_load_lds_dwordx4 v[140:141], off
	v_lshl_add_u64 v[140:141], s[24:25], 0, v[138:139]
	s_add_i32 m0, s30, 0xe000
	s_nop 0
	global_load_lds_dwordx4 v[140:141], off
	s_waitcnt vmcnt(8)
	s_waitcnt lgkmcnt(0)
	s_barrier
	v_mfma_f32_16x16x32_bf16 v[126:129], v[150:153], v[182:185], v[126:129]
	v_mfma_f32_16x16x32_bf16 v[126:129], v[154:157], v[194:197], v[126:129]
	v_mfma_f32_16x16x32_bf16 v[122:125], v[158:161], v[182:185], v[122:125]
	v_mfma_f32_16x16x32_bf16 v[122:125], v[162:165], v[194:197], v[122:125]
	v_mfma_f32_16x16x32_bf16 v[106:109], v[158:161], v[198:201], v[106:109]
	v_mfma_f32_16x16x32_bf16 v[106:109], v[162:165], v[202:205], v[106:109]
	v_mfma_f32_16x16x32_bf16 v[110:113], v[150:153], v[198:201], v[110:113]
	v_mfma_f32_16x16x32_bf16 v[110:113], v[154:157], v[202:205], v[110:113]
	v_mfma_f32_16x16x32_bf16 v[94:97], v[150:153], v[206:209], v[94:97]
	v_mfma_f32_16x16x32_bf16 v[94:97], v[154:157], v[210:213], v[94:97]
	v_mfma_f32_16x16x32_bf16 v[90:93], v[158:161], v[206:209], v[90:93]
	v_mfma_f32_16x16x32_bf16 v[90:93], v[162:165], v[210:213], v[90:93]
	v_mfma_f32_16x16x32_bf16 v[74:77], v[158:161], v[214:217], v[74:77]
	v_mfma_f32_16x16x32_bf16 v[74:77], v[162:165], v[218:221], v[74:77]
	v_mfma_f32_16x16x32_bf16 v[78:81], v[150:153], v[214:217], v[78:81]
	v_mfma_f32_16x16x32_bf16 v[78:81], v[154:157], v[218:221], v[78:81]
	v_mfma_f32_16x16x32_bf16 v[118:121], v[166:169], v[182:185], v[118:121]
	v_mfma_f32_16x16x32_bf16 v[118:121], v[170:173], v[194:197], v[118:121]
	v_mfma_f32_16x16x32_bf16 v[114:117], v[174:177], v[182:185], v[114:117]
	v_mfma_f32_16x16x32_bf16 v[114:117], v[178:181], v[194:197], v[114:117]
	v_mfma_f32_16x16x32_bf16 v[98:101], v[174:177], v[198:201], v[98:101]
	v_mfma_f32_16x16x32_bf16 v[98:101], v[178:181], v[202:205], v[98:101]
	v_mfma_f32_16x16x32_bf16 v[102:105], v[166:169], v[198:201], v[102:105]
	v_mfma_f32_16x16x32_bf16 v[102:105], v[170:173], v[202:205], v[102:105]
	v_mfma_f32_16x16x32_bf16 v[86:89], v[166:169], v[206:209], v[86:89]
	v_mfma_f32_16x16x32_bf16 v[86:89], v[170:173], v[210:213], v[86:89]
	v_mfma_f32_16x16x32_bf16 v[82:85], v[174:177], v[206:209], v[82:85]
	v_mfma_f32_16x16x32_bf16 v[82:85], v[178:181], v[210:213], v[82:85]
	v_mfma_f32_16x16x32_bf16 v[66:69], v[174:177], v[214:217], v[66:69]
	v_mfma_f32_16x16x32_bf16 v[66:69], v[178:181], v[218:221], v[66:69]
	v_mfma_f32_16x16x32_bf16 v[70:73], v[166:169], v[214:217], v[70:73]
	v_mfma_f32_16x16x32_bf16 v[70:73], v[170:173], v[218:221], v[70:73]
	s_barrier
	s_add_i32 s45, s45, s9
	v_lshl_add_u64 v[140:141], s[26:27], 0, v[0:1]
	s_mov_b32 m0, s45
	ds_read_b128 v[182:185], v149 offset:16384
	ds_read_b128 v[194:197], v149 offset:17408
	ds_read_b128 v[198:201], v149 offset:18432
	ds_read_b128 v[202:205], v149 offset:19456
	ds_read_b128 v[206:209], v149 offset:20480
	ds_read_b128 v[210:213], v149 offset:21504
	ds_read_b128 v[214:217], v149 offset:22528
	ds_read_b128 v[218:221], v149 offset:23552
	global_load_lds_dwordx4 v[140:141], off
	s_add_i32 m0, s45, 0x2000
	s_add_u32 s48, s26, 0x80000
	v_lshl_add_u64 v[186:187], s[26:27], 0, v[130:131]
	s_addc_u32 s49, s27, 0
	s_add_i32 s45, s47, s9
	global_load_lds_dwordx4 v[186:187], off
	v_lshl_add_u64 v[188:189], s[48:49], 0, v[0:1]
	s_mov_b32 m0, s45
	v_lshl_add_u64 v[190:191], s[28:29], 0, v[132:133]
	global_load_lds_dwordx4 v[188:189], off
	v_lshl_add_u64 v[188:189], s[48:49], 0, v[130:131]
	s_add_i32 m0, s45, 0x2000
	s_nop 0
	global_load_lds_dwordx4 v[188:189], off
	v_lshl_add_u64 v[188:189], s[28:29], 0, v[134:135]
	s_mov_b32 m0, s30
	s_nop 0
	global_load_lds_dwordx4 v[188:189], off
	s_mov_b32 m0, s31
	s_nop 0
	global_load_lds_dwordx4 v[190:191], off
	s_waitcnt vmcnt(8)
	s_waitcnt lgkmcnt(0)
	s_barrier
; #define PG8_STAGE(bufoff, gbase, voff) do { _Pragma("unroll") for (int _i = 0; _i < 2; ++_i) \
;         __builtin_amdgcn_global_load_lds((const unsigned*)((const char*)(gbase) + (voff)[_i]), (LAS unsigned*)(lds + (bufoff) + ldsw + _i * 8192), 16, 0, 0); } while (0)
; #define PG8_LDA(dst, b, h) do { _Pragma("unroll") for (int m = 0; m < 4; ++m) _Pragma("unroll") for (int k = 0; k < 2; ++k) dst[m][k] = *(const LAS bf16x8*)(lds + PG8_SA(b, h) + aoff + m * 2048 + k * 1024); } while (0)
; #define PG8_LDB(dst, b, h) do { _Pragma("unroll") for (int n = 0; n < 2; ++n) _Pragma("unroll") for (int k = 0; k < 2; ++k) dst[n][k] = *(const LAS bf16x8*)(lds + PG8_SB(b, h) + boff + n * 2048 + k * 1024); } while (0)
; #define PG8_MMA(ai, bj, At, Bt) do { __builtin_amdgcn_s_setprio(1); _Pragma("unroll") for (int m = 0; m < 4; ++m) _Pragma("unroll") for (int n = 0; n < 2; ++n) _Pragma("unroll") for (int k = 0; k < 2; ++k) \
;         acc[ai][bj][m][n] = __builtin_amdgcn_mfma_f32_16x16x32_bf16(Bt[n][k], At[m][k], acc[ai][bj][m][n], 0, 0, 0); __builtin_amdgcn_s_setprio(0); } while (0)
; #define PG8_WAIT_V(n) asm volatile("s_waitcnt vmcnt(" #n ")" ::: "memory")
; #define PG8_WAIT_L(n) asm volatile("s_waitcnt lgkmcnt(" #n ")" ::: "memory")
; #define PG8_BAR __builtin_amdgcn_s_barrier()
; #define PG8_SCHED __builtin_amdgcn_sched_barrier(0)
; template <class Epi, class Sched, bool ALIGN_EPI = false, bool SP2 = false>
; __device__ __forceinline__ void gemm_phase(LAS unsigned char* lds, const Gemm g, const Sched& S, const Epi& E) {
;     ...
;             PG8_WAIT_V(8); PG8_WAIT_L(0); PG8_BAR; PG8_MMA(1, 0, At, B0); PG8_MMA(1, 1, At, B1); PG8_BAR; PG8_SCHED;
;             PG8_LDB(B0, 1, 0); PG8_LDB(B1, 1, 1); PG8_SCHED; PG8_LDA(At, 1, 0); PG8_STAGE(PG8_SA(0, 1), a2 + hstep, voffA);
;             PG8_WAIT_V(8); PG8_WAIT_L(0); PG8_BAR; PG8_MMA(0, 0, At, B0); PG8_MMA(0, 1, At, B1); PG8_BAR; PG8_SCHED;
	v_mfma_f32_16x16x32_bf16 v[62:65], v[150:153], v[182:185], v[62:65]
	v_mfma_f32_16x16x32_bf16 v[62:65], v[154:157], v[194:197], v[62:65]
	v_mfma_f32_16x16x32_bf16 v[58:61], v[158:161], v[182:185], v[58:61]
	v_mfma_f32_16x16x32_bf16 v[58:61], v[162:165], v[194:197], v[58:61]
	v_mfma_f32_16x16x32_bf16 v[42:45], v[158:161], v[198:201], v[42:45]
	v_mfma_f32_16x16x32_bf16 v[42:45], v[162:165], v[202:205], v[42:45]
	v_mfma_f32_16x16x32_bf16 v[46:49], v[150:153], v[198:201], v[46:49]
	v_mfma_f32_16x16x32_bf16 v[46:49], v[154:157], v[202:205], v[46:49]
	v_mfma_f32_16x16x32_bf16 v[30:33], v[150:153], v[206:209], v[30:33]
	v_mfma_f32_16x16x32_bf16 v[30:33], v[154:157], v[210:213], v[30:33]
	v_mfma_f32_16x16x32_bf16 v[26:29], v[158:161], v[206:209], v[26:29]
	v_mfma_f32_16x16x32_bf16 v[26:29], v[162:165], v[210:213], v[26:29]
	v_mfma_f32_16x16x32_bf16 v[10:13], v[158:161], v[214:217], v[10:13]
	v_mfma_f32_16x16x32_bf16 v[10:13], v[162:165], v[218:221], v[10:13]
	v_mfma_f32_16x16x32_bf16 v[14:17], v[150:153], v[214:217], v[14:17]
	v_mfma_f32_16x16x32_bf16 v[14:17], v[154:157], v[218:221], v[14:17]
	v_mfma_f32_16x16x32_bf16 v[54:57], v[166:169], v[182:185], v[54:57]
	v_mfma_f32_16x16x32_bf16 v[54:57], v[170:173], v[194:197], v[54:57]
	v_mfma_f32_16x16x32_bf16 v[50:53], v[174:177], v[182:185], v[50:53]
	v_mfma_f32_16x16x32_bf16 v[50:53], v[178:181], v[194:197], v[50:53]
	v_mfma_f32_16x16x32_bf16 v[34:37], v[174:177], v[198:201], v[34:37]
	v_mfma_f32_16x16x32_bf16 v[34:37], v[178:181], v[202:205], v[34:37]
	v_mfma_f32_16x16x32_bf16 v[38:41], v[166:169], v[198:201], v[38:41]
	v_mfma_f32_16x16x32_bf16 v[38:41], v[170:173], v[202:205], v[38:41]
	v_mfma_f32_16x16x32_bf16 v[22:25], v[166:169], v[206:209], v[22:25]
	v_mfma_f32_16x16x32_bf16 v[22:25], v[170:173], v[210:213], v[22:25]
	v_mfma_f32_16x16x32_bf16 v[18:21], v[174:177], v[206:209], v[18:21]
	v_mfma_f32_16x16x32_bf16 v[18:21], v[178:181], v[210:213], v[18:21]
	v_mfma_f32_16x16x32_bf16 v[2:5], v[174:177], v[214:217], v[2:5]
	v_mfma_f32_16x16x32_bf16 v[2:5], v[178:181], v[218:221], v[2:5]
	v_mfma_f32_16x16x32_bf16 v[6:9], v[166:169], v[214:217], v[6:9]
	v_mfma_f32_16x16x32_bf16 v[6:9], v[170:173], v[218:221], v[6:9]
	s_barrier
	s_add_i32 s45, 0, 0x18000
	v_add_u32_e32 v142, s45, v145
	s_add_i32 s47, 0, 0x1c000
	ds_read_b128 v[150:153], v142
	ds_read_b128 v[154:157], v142 offset:1024
	ds_read_b128 v[158:161], v142 offset:2048
	ds_read_b128 v[162:165], v142 offset:3072
	v_add_u32_e32 v142, s47, v145
	ds_read_b128 v[166:169], v142
	ds_read_b128 v[170:173], v142 offset:1024
	ds_read_b128 v[174:177], v142 offset:2048
	ds_read_b128 v[178:181], v142 offset:3072
	s_add_u32 s28, s28, 0x80000
	s_addc_u32 s29, s29, 0
	s_mov_b32 m0, s38
	v_lshl_add_u64 v[192:193], s[28:29], 0, v[134:135]
	ds_read_b128 v[182:185], v149 offset:32768
	ds_read_b128 v[194:197], v149 offset:33792
	ds_read_b128 v[198:201], v149 offset:34816
	ds_read_b128 v[202:205], v149 offset:35840
	ds_read_b128 v[206:209], v149 offset:36864
	ds_read_b128 v[210:213], v149 offset:37888
	ds_read_b128 v[214:217], v149 offset:38912
	ds_read_b128 v[218:221], v149 offset:39936
	global_load_lds_dwordx4 v[192:193], off
	v_lshl_add_u64 v[192:193], s[28:29], 0, v[132:133]
	s_mov_b32 m0, s39
	s_nop 0
	global_load_lds_dwordx4 v[192:193], off
	s_waitcnt vmcnt(8)
	s_waitcnt lgkmcnt(0)
	s_barrier
	v_mfma_f32_16x16x32_bf16 v[126:129], v[150:153], v[182:185], v[126:129]
	v_mfma_f32_16x16x32_bf16 v[126:129], v[154:157], v[194:197], v[126:129]
	v_mfma_f32_16x16x32_bf16 v[122:125], v[158:161], v[182:185], v[122:125]
	v_mfma_f32_16x16x32_bf16 v[122:125], v[162:165], v[194:197], v[122:125]
	v_mfma_f32_16x16x32_bf16 v[106:109], v[158:161], v[198:201], v[106:109]
	v_mfma_f32_16x16x32_bf16 v[106:109], v[162:165], v[202:205], v[106:109]
	v_mfma_f32_16x16x32_bf16 v[110:113], v[150:153], v[198:201], v[110:113]
	v_mfma_f32_16x16x32_bf16 v[110:113], v[154:157], v[202:205], v[110:113]
	v_mfma_f32_16x16x32_bf16 v[94:97], v[150:153], v[206:209], v[94:97]
	v_mfma_f32_16x16x32_bf16 v[94:97], v[154:157], v[210:213], v[94:97]
	v_mfma_f32_16x16x32_bf16 v[90:93], v[158:161], v[206:209], v[90:93]
	v_mfma_f32_16x16x32_bf16 v[90:93], v[162:165], v[210:213], v[90:93]
	v_mfma_f32_16x16x32_bf16 v[74:77], v[158:161], v[214:217], v[74:77]
	v_mfma_f32_16x16x32_bf16 v[74:77], v[162:165], v[218:221], v[74:77]
	v_mfma_f32_16x16x32_bf16 v[78:81], v[150:153], v[214:217], v[78:81]
	v_mfma_f32_16x16x32_bf16 v[78:81], v[154:157], v[218:221], v[78:81]
	v_mfma_f32_16x16x32_bf16 v[118:121], v[166:169], v[182:185], v[118:121]
	v_mfma_f32_16x16x32_bf16 v[118:121], v[170:173], v[194:197], v[118:121]
	v_mfma_f32_16x16x32_bf16 v[114:117], v[174:177], v[182:185], v[114:117]
	v_mfma_f32_16x16x32_bf16 v[114:117], v[178:181], v[194:197], v[114:117]
	v_mfma_f32_16x16x32_bf16 v[98:101], v[174:177], v[198:201], v[98:101]
	v_mfma_f32_16x16x32_bf16 v[98:101], v[178:181], v[202:205], v[98:101]
	v_mfma_f32_16x16x32_bf16 v[102:105], v[166:169], v[198:201], v[102:105]
	v_mfma_f32_16x16x32_bf16 v[102:105], v[170:173], v[202:205], v[102:105]
	v_mfma_f32_16x16x32_bf16 v[86:89], v[166:169], v[206:209], v[86:89]
	v_mfma_f32_16x16x32_bf16 v[86:89], v[170:173], v[210:213], v[86:89]
	v_mfma_f32_16x16x32_bf16 v[82:85], v[174:177], v[206:209], v[82:85]
	v_mfma_f32_16x16x32_bf16 v[82:85], v[178:181], v[210:213], v[82:85]
	v_mfma_f32_16x16x32_bf16 v[66:69], v[174:177], v[214:217], v[66:69]
	v_mfma_f32_16x16x32_bf16 v[66:69], v[178:181], v[218:221], v[66:69]
	v_mfma_f32_16x16x32_bf16 v[70:73], v[166:169], v[214:217], v[70:73]
	v_mfma_f32_16x16x32_bf16 v[70:73], v[170:173], v[218:221], v[70:73]
	s_barrier
; #define PG8_STAGE(bufoff, gbase, voff) do { _Pragma("unroll") for (int _i = 0; _i < 2; ++_i) \
;         __builtin_amdgcn_global_load_lds((const unsigned*)((const char*)(gbase) + (voff)[_i]), (LAS unsigned*)(lds + (bufoff) + ldsw + _i * 8192), 16, 0, 0); } while (0)
; #define PG8_LDA(dst, b, h) do { _Pragma("unroll") for (int m = 0; m < 4; ++m) _Pragma("unroll") for (int k = 0; k < 2; ++k) dst[m][k] = *(const LAS bf16x8*)(lds + PG8_SA(b, h) + aoff + m * 2048 + k * 1024); } while (0)
; #define PG8_MMA(ai, bj, At, Bt) do { __builtin_amdgcn_s_setprio(1); _Pragma("unroll") for (int m = 0; m < 4; ++m) _Pragma("unroll") for (int n = 0; n < 2; ++n) _Pragma("unroll") for (int k = 0; k < 2; ++k) \
;         acc[ai][bj][m][n] = __builtin_amdgcn_mfma_f32_16x16x32_bf16(Bt[n][k], At[m][k], acc[ai][bj][m][n], 0, 0, 0); __builtin_amdgcn_s_setprio(0); } while (0)
; #define PG8_WAIT_V(n) asm volatile("s_waitcnt vmcnt(" #n ")" ::: "memory")
; #define PG8_WAIT_L(n) asm volatile("s_waitcnt lgkmcnt(" #n ")" ::: "memory")
; #define PG8_BAR __builtin_amdgcn_s_barrier()
; #define PG8_SCHED __builtin_amdgcn_sched_barrier(0)
; template <class Epi, class Sched, bool ALIGN_EPI = false, bool SP2 = false>
; __device__ __forceinline__ void gemm_phase(LAS unsigned char* lds, const Gemm g, const Sched& S, const Epi& E) {
;     ...
;         for (int t = 0; t < nt; t += 2) {
;             const bool last = (t == nt - 2);
;             const char* a1 = cA + (size_t)(t + 1) * kstep;
;             const char* a2 = last ? nA : cA + (size_t)(t + 2) * kstep; const char* b2 = last ? nB : cB + (size_t)(t + 2) * kstep;
;             const char* a3 = a2 + kstep; const char* b3 = b2 + kstep;
;             if (last && has_next) S.a_ready(nxt);
;     ...
;             PG8_WAIT_V(8); PG8_WAIT_L(0); PG8_BAR; PG8_MMA(0, 0, At, B0); PG8_MMA(0, 1, At, B1); PG8_BAR; PG8_SCHED;
;             PG8_LDA(At, 1, 1); PG8_STAGE(PG8_SB(1, 0), b3, voffB); PG8_STAGE(PG8_SB(1, 1), b3 + hstep, voffB); PG8_STAGE(PG8_SA(1, 0), a3, voffA);
;             PG8_WAIT_V(8); PG8_WAIT_L(0); PG8_BAR; PG8_MMA(1, 0, At, B0); PG8_MMA(1, 1, At, B1); PG8_BAR; PG8_SCHED;
	s_add_i32 s28, s45, s9
	v_lshl_add_u64 v[140:141], v[140:141], 0, s[12:13]
	s_mov_b32 m0, s28
	ds_read_b128 v[182:185], v149 offset:49152
	ds_read_b128 v[194:197], v149 offset:50176
	ds_read_b128 v[198:201], v149 offset:51200
	ds_read_b128 v[202:205], v149 offset:52224
	ds_read_b128 v[206:209], v149 offset:53248
	ds_read_b128 v[210:213], v149 offset:54272
	ds_read_b128 v[214:217], v149 offset:55296
	ds_read_b128 v[218:221], v149 offset:56320
	global_load_lds_dwordx4 v[140:141], off
	s_add_i32 m0, s28, 0x2000
	s_add_u32 s26, s26, 0x80080
	v_lshl_add_u64 v[140:141], v[186:187], 0, s[12:13]
	s_addc_u32 s27, s27, 0
	s_add_i32 s28, s47, s9
	global_load_lds_dwordx4 v[140:141], off
	v_lshl_add_u64 v[140:141], s[26:27], 0, v[0:1]
	s_mov_b32 m0, s28
	s_nop 0
	global_load_lds_dwordx4 v[140:141], off
	v_lshl_add_u64 v[140:141], s[26:27], 0, v[130:131]
	s_add_i32 m0, s28, 0x2000
	s_nop 0
	global_load_lds_dwordx4 v[140:141], off
	v_lshl_add_u64 v[140:141], v[188:189], 0, s[12:13]
	s_mov_b32 m0, s40
	s_nop 0
	global_load_lds_dwordx4 v[140:141], off
	v_lshl_add_u64 v[140:141], v[190:191], 0, s[12:13]
	s_mov_b32 m0, s41
	s_nop 0
	global_load_lds_dwordx4 v[140:141], off
	s_waitcnt vmcnt(8)
	s_waitcnt lgkmcnt(0)
	s_barrier
	v_mfma_f32_16x16x32_bf16 v[62:65], v[150:153], v[182:185], v[62:65]
	v_mfma_f32_16x16x32_bf16 v[62:65], v[154:157], v[194:197], v[62:65]
	v_mfma_f32_16x16x32_bf16 v[58:61], v[158:161], v[182:185], v[58:61]
	v_mfma_f32_16x16x32_bf16 v[58:61], v[162:165], v[194:197], v[58:61]
	v_mfma_f32_16x16x32_bf16 v[42:45], v[158:161], v[198:201], v[42:45]
	v_mfma_f32_16x16x32_bf16 v[42:45], v[162:165], v[202:205], v[42:45]
	v_mfma_f32_16x16x32_bf16 v[46:49], v[150:153], v[198:201], v[46:49]
	v_mfma_f32_16x16x32_bf16 v[46:49], v[154:157], v[202:205], v[46:49]
	v_mfma_f32_16x16x32_bf16 v[30:33], v[150:153], v[206:209], v[30:33]
	v_mfma_f32_16x16x32_bf16 v[30:33], v[154:157], v[210:213], v[30:33]
	v_mfma_f32_16x16x32_bf16 v[26:29], v[158:161], v[206:209], v[26:29]
	v_mfma_f32_16x16x32_bf16 v[26:29], v[162:165], v[210:213], v[26:29]
	v_mfma_f32_16x16x32_bf16 v[10:13], v[158:161], v[214:217], v[10:13]
	v_mfma_f32_16x16x32_bf16 v[10:13], v[162:165], v[218:221], v[10:13]
	v_mfma_f32_16x16x32_bf16 v[14:17], v[150:153], v[214:217], v[14:17]
	v_mfma_f32_16x16x32_bf16 v[14:17], v[154:157], v[218:221], v[14:17]
	v_mfma_f32_16x16x32_bf16 v[54:57], v[166:169], v[182:185], v[54:57]
	v_mfma_f32_16x16x32_bf16 v[54:57], v[170:173], v[194:197], v[54:57]
	v_mfma_f32_16x16x32_bf16 v[50:53], v[174:177], v[182:185], v[50:53]
	v_mfma_f32_16x16x32_bf16 v[50:53], v[178:181], v[194:197], v[50:53]
	v_mfma_f32_16x16x32_bf16 v[34:37], v[174:177], v[198:201], v[34:37]
	v_mfma_f32_16x16x32_bf16 v[34:37], v[178:181], v[202:205], v[34:37]
	v_mfma_f32_16x16x32_bf16 v[38:41], v[166:169], v[198:201], v[38:41]
	v_mfma_f32_16x16x32_bf16 v[38:41], v[170:173], v[202:205], v[38:41]
	v_mfma_f32_16x16x32_bf16 v[22:25], v[166:169], v[206:209], v[22:25]
	v_mfma_f32_16x16x32_bf16 v[22:25], v[170:173], v[210:213], v[22:25]
	v_mfma_f32_16x16x32_bf16 v[18:21], v[174:177], v[206:209], v[18:21]
	v_mfma_f32_16x16x32_bf16 v[18:21], v[178:181], v[210:213], v[18:21]
	v_mfma_f32_16x16x32_bf16 v[2:5], v[174:177], v[214:217], v[2:5]
	v_mfma_f32_16x16x32_bf16 v[2:5], v[178:181], v[218:221], v[2:5]
	v_mfma_f32_16x16x32_bf16 v[6:9], v[166:169], v[214:217], v[6:9]
	v_mfma_f32_16x16x32_bf16 v[6:9], v[170:173], v[218:221], v[6:9]
	s_barrier
	s_add_i32 s44, s44, 2
	s_add_u32 s24, s24, 0x100
	s_addc_u32 s25, s25, 0
	s_add_u32 s35, s35, 0x100
	s_addc_u32 s43, s43, 0
	s_cmp_gt_u32 s44, 29
	s_cbranch_scc0 .LBB0_173
	s_and_b64 vcc, exec, s[4:5]
	s_cbranch_vccz .LBB0_176
	s_barrier

; #define PG8_STAGE(bufoff, gbase, voff) do { _Pragma("unroll") for (int _i = 0; _i < 2; ++_i) \
;         __builtin_amdgcn_global_load_lds((const unsigned*)((const char*)(gbase) + (voff)[_i]), (LAS unsigned*)(lds + (bufoff) + ldsw + _i * 8192), 16, 0, 0); } while (0)
; #define PG8_LDA(dst, b, h) do { _Pragma("unroll") for (int m = 0; m < 4; ++m) _Pragma("unroll") for (int k = 0; k < 2; ++k) dst[m][k] = *(const LAS bf16x8*)(lds + PG8_SA(b, h) + aoff + m * 2048 + k * 1024); } while (0)
; #define PG8_LDB(dst, b, h) do { _Pragma("unroll") for (int n = 0; n < 2; ++n) _Pragma("unroll") for (int k = 0; k < 2; ++k) dst[n][k] = *(const LAS bf16x8*)(lds + PG8_SB(b, h) + boff + n * 2048 + k * 1024); } while (0)
; #define PG8_MMA(ai, bj, At, Bt) do { __builtin_amdgcn_s_setprio(1); _Pragma("unroll") for (int m = 0; m < 4; ++m) _Pragma("unroll") for (int n = 0; n < 2; ++n) _Pragma("unroll") for (int k = 0; k < 2; ++k) \
;         acc[ai][bj][m][n] = __builtin_amdgcn_mfma_f32_16x16x32_bf16(Bt[n][k], At[m][k], acc[ai][bj][m][n], 0, 0, 0); __builtin_amdgcn_s_setprio(0); } while (0)
; #define PG8_WAIT_V(n) asm volatile("s_waitcnt vmcnt(" #n ")" ::: "memory")
; #define PG8_WAIT_L(n) asm volatile("s_waitcnt lgkmcnt(" #n ")" ::: "memory")
; template <class Epi, class Sched, bool ALIGN_EPI = false, bool SP2 = false>
; __device__ __forceinline__ void gemm_phase(LAS unsigned char* lds, const Gemm g, const Sched& S, const Epi& E) {
;     ...
;         for (int t = 0; t < nt; t += 2) {
;             const bool last = (t == nt - 2);
;             const char* a1 = cA + (size_t)(t + 1) * kstep;
;             const char* a2 = last ? nA : cA + (size_t)(t + 2) * kstep; const char* b2 = last ? nB : cB + (size_t)(t + 2) * kstep;
;             const char* a3 = a2 + kstep; const char* b3 = b2 + kstep;
;             if (last && has_next) S.a_ready(nxt);
;             if constexpr (SP2) {
;             PG8_LDB(B0, 0, 0); PG8_LDB(B1, 0, 1); PG8_SCHED; PG8_LDA(At, 0, 0); PG8_STAGE(PG8_SA(1, 1), a1 + hstep, voffA);
;             PG8_WAIT_V(8); PG8_WAIT_L(0); PG8_BAR; PG8_MMA(0, 0, At, B0); PG8_MMA(0, 1, At, B1); PG8_BAR; PG8_SCHED;
;             PG8_LDA(At, 0, 1); PG8_STAGE(PG8_SB(0, 0), b2, voffB); PG8_STAGE(PG8_SB(0, 1), b2 + hstep, voffB); PG8_STAGE(PG8_SA(0, 0), a2, voffA);
;             PG8_WAIT_V(8); PG8_WAIT_L(0); PG8_BAR; PG8_MMA(1, 0, At, B0); PG8_MMA(1, 1, At, B1); PG8_BAR; PG8_SCHED;
.LBB0_257:
	s_add_u32 s24, s22, 0x100
	s_addc_u32 s25, s23, 0
	s_add_i32 s50, 0, 0x10000
	s_cmpk_eq_i32 s49, 0x54
	s_cselect_b32 s29, s1, s25
	s_cselect_b32 s28, s0, s24
	s_cselect_b32 s27, s21, s48
	s_cselect_b32 s26, s20, s47
	s_add_i32 s51, 0, 0x14000
	v_add_u32_e32 v126, s50, v247
	v_add_u32_e32 v158, s51, v247
	ds_read_b128 v[90:93], v126
	ds_read_b128 v[102:105], v126 offset:1024
	ds_read_b128 v[114:117], v126 offset:2048
	ds_read_b128 v[126:129], v126 offset:3072
	ds_read_b128 v[138:141], v158
	ds_read_b128 v[142:145], v158 offset:1024
	ds_read_b128 v[154:157], v158 offset:2048
	ds_read_b128 v[158:161], v158 offset:3072
	v_lshl_add_u64 v[186:187], s[22:23], 0, v[200:201]
	s_add_i32 m0, s6, 0xc000
	ds_read_b128 v[162:165], v249
	ds_read_b128 v[166:169], v249 offset:1024
	ds_read_b128 v[170:173], v249 offset:2048
	ds_read_b128 v[174:177], v249 offset:3072
	ds_read_b128 v[178:181], v249 offset:4096
	ds_read_b128 v[182:185], v249 offset:5120
	ds_read_b128 v[204:207], v249 offset:6144
	ds_read_b128 v[208:211], v249 offset:7168
	global_load_lds_dwordx4 v[186:187], off
	v_lshl_add_u64 v[186:187], s[22:23], 0, v[202:203]
	s_add_i32 m0, s6, 0xe000
	s_nop 0
	global_load_lds_dwordx4 v[186:187], off
	s_waitcnt vmcnt(8)
	s_waitcnt lgkmcnt(0)
	s_barrier
	v_mfma_f32_16x16x32_bf16 v[150:153], v[90:93], v[162:165], v[150:153]
	v_mfma_f32_16x16x32_bf16 v[150:153], v[102:105], v[166:169], v[150:153]
	v_mfma_f32_16x16x32_bf16 v[146:149], v[114:117], v[162:165], v[146:149]
	v_mfma_f32_16x16x32_bf16 v[146:149], v[126:129], v[166:169], v[146:149]
	v_mfma_f32_16x16x32_bf16 v[118:121], v[114:117], v[170:173], v[118:121]
	v_mfma_f32_16x16x32_bf16 v[118:121], v[126:129], v[174:177], v[118:121]
	v_mfma_f32_16x16x32_bf16 v[122:125], v[90:93], v[170:173], v[122:125]
	v_mfma_f32_16x16x32_bf16 v[122:125], v[102:105], v[174:177], v[122:125]
	v_mfma_f32_16x16x32_bf16 v[98:101], v[90:93], v[178:181], v[98:101]
	v_mfma_f32_16x16x32_bf16 v[98:101], v[102:105], v[182:185], v[98:101]
	v_mfma_f32_16x16x32_bf16 v[94:97], v[114:117], v[178:181], v[94:97]
	v_mfma_f32_16x16x32_bf16 v[94:97], v[126:129], v[182:185], v[94:97]
	v_mfma_f32_16x16x32_bf16 v[74:77], v[114:117], v[204:207], v[74:77]
	v_mfma_f32_16x16x32_bf16 v[74:77], v[126:129], v[208:211], v[74:77]
	v_mfma_f32_16x16x32_bf16 v[78:81], v[90:93], v[204:207], v[78:81]
	v_mfma_f32_16x16x32_bf16 v[78:81], v[102:105], v[208:211], v[78:81]
	v_mfma_f32_16x16x32_bf16 v[134:137], v[138:141], v[162:165], v[134:137]
	v_mfma_f32_16x16x32_bf16 v[134:137], v[142:145], v[166:169], v[134:137]
	v_mfma_f32_16x16x32_bf16 v[130:133], v[154:157], v[162:165], v[130:133]
	v_mfma_f32_16x16x32_bf16 v[130:133], v[158:161], v[166:169], v[130:133]
	v_mfma_f32_16x16x32_bf16 v[106:109], v[154:157], v[170:173], v[106:109]
	v_mfma_f32_16x16x32_bf16 v[106:109], v[158:161], v[174:177], v[106:109]
	v_mfma_f32_16x16x32_bf16 v[110:113], v[138:141], v[170:173], v[110:113]
	v_mfma_f32_16x16x32_bf16 v[110:113], v[142:145], v[174:177], v[110:113]
	v_mfma_f32_16x16x32_bf16 v[86:89], v[138:141], v[178:181], v[86:89]
	v_mfma_f32_16x16x32_bf16 v[86:89], v[142:145], v[182:185], v[86:89]
	v_mfma_f32_16x16x32_bf16 v[82:85], v[154:157], v[178:181], v[82:85]
	v_mfma_f32_16x16x32_bf16 v[82:85], v[158:161], v[182:185], v[82:85]
	v_mfma_f32_16x16x32_bf16 v[66:69], v[154:157], v[204:207], v[66:69]
	v_mfma_f32_16x16x32_bf16 v[66:69], v[158:161], v[208:211], v[66:69]
	v_mfma_f32_16x16x32_bf16 v[70:73], v[138:141], v[204:207], v[70:73]
	v_mfma_f32_16x16x32_bf16 v[70:73], v[142:145], v[208:211], v[70:73]
	s_barrier
	s_add_i32 s22, s50, s2
	v_lshl_add_u64 v[186:187], s[26:27], 0, v[0:1]
	s_mov_b32 m0, s22
	ds_read_b128 v[162:165], v249 offset:16384
	ds_read_b128 v[166:169], v249 offset:17408
	ds_read_b128 v[170:173], v249 offset:18432
	ds_read_b128 v[174:177], v249 offset:19456
	ds_read_b128 v[178:181], v249 offset:20480
	ds_read_b128 v[182:185], v249 offset:21504
	ds_read_b128 v[204:207], v249 offset:22528
	ds_read_b128 v[208:211], v249 offset:23552
	global_load_lds_dwordx4 v[186:187], off
	s_add_i32 m0, s22, 0x2000
	s_add_u32 s22, s26, 0x160000
	v_lshl_add_u64 v[188:189], s[26:27], 0, v[194:195]
	s_addc_u32 s23, s27, 0
	s_add_i32 s50, s51, s2
	global_load_lds_dwordx4 v[188:189], off
	v_lshl_add_u64 v[190:191], s[22:23], 0, v[0:1]
	s_mov_b32 m0, s50
	v_lshl_add_u64 v[192:193], s[28:29], 0, v[196:197]
	global_load_lds_dwordx4 v[190:191], off
	v_lshl_add_u64 v[190:191], s[22:23], 0, v[194:195]
	s_add_i32 m0, s50, 0x2000
	s_nop 0
	global_load_lds_dwordx4 v[190:191], off
	v_lshl_add_u64 v[190:191], s[28:29], 0, v[198:199]
	s_mov_b32 m0, s6
	s_nop 0
	global_load_lds_dwordx4 v[190:191], off
	s_mov_b32 m0, s7
	s_nop 0
	global_load_lds_dwordx4 v[192:193], off
	s_waitcnt vmcnt(8)
	s_waitcnt lgkmcnt(0)
	s_barrier
; #define PG8_STAGE(bufoff, gbase, voff) do { _Pragma("unroll") for (int _i = 0; _i < 2; ++_i) \
;         __builtin_amdgcn_global_load_lds((const unsigned*)((const char*)(gbase) + (voff)[_i]), (LAS unsigned*)(lds + (bufoff) + ldsw + _i * 8192), 16, 0, 0); } while (0)
; #define PG8_LDA(dst, b, h) do { _Pragma("unroll") for (int m = 0; m < 4; ++m) _Pragma("unroll") for (int k = 0; k < 2; ++k) dst[m][k] = *(const LAS bf16x8*)(lds + PG8_SA(b, h) + aoff + m * 2048 + k * 1024); } while (0)
; #define PG8_LDB(dst, b, h) do { _Pragma("unroll") for (int n = 0; n < 2; ++n) _Pragma("unroll") for (int k = 0; k < 2; ++k) dst[n][k] = *(const LAS bf16x8*)(lds + PG8_SB(b, h) + boff + n * 2048 + k * 1024); } while (0)
; #define PG8_MMA(ai, bj, At, Bt) do { __builtin_amdgcn_s_setprio(1); _Pragma("unroll") for (int m = 0; m < 4; ++m) _Pragma("unroll") for (int n = 0; n < 2; ++n) _Pragma("unroll") for (int k = 0; k < 2; ++k) \
;         acc[ai][bj][m][n] = __builtin_amdgcn_mfma_f32_16x16x32_bf16(Bt[n][k], At[m][k], acc[ai][bj][m][n], 0, 0, 0); __builtin_amdgcn_s_setprio(0); } while (0)
; #define PG8_WAIT_V(n) asm volatile("s_waitcnt vmcnt(" #n ")" ::: "memory")
; #define PG8_WAIT_L(n) asm volatile("s_waitcnt lgkmcnt(" #n ")" ::: "memory")
; #define PG8_BAR __builtin_amdgcn_s_barrier()
; #define PG8_SCHED __builtin_amdgcn_sched_barrier(0)
; template <class Epi, class Sched, bool ALIGN_EPI = false, bool SP2 = false>
; __device__ __forceinline__ void gemm_phase(LAS unsigned char* lds, const Gemm g, const Sched& S, const Epi& E) {
;     ...
;             PG8_WAIT_V(8); PG8_WAIT_L(0); PG8_BAR; PG8_MMA(1, 0, At, B0); PG8_MMA(1, 1, At, B1); PG8_BAR; PG8_SCHED;
;             PG8_LDB(B0, 1, 0); PG8_LDB(B1, 1, 1); PG8_SCHED; PG8_LDA(At, 1, 0); PG8_STAGE(PG8_SA(0, 1), a2 + hstep, voffA);
;             PG8_WAIT_V(8); PG8_WAIT_L(0); PG8_BAR; PG8_MMA(0, 0, At, B0); PG8_MMA(0, 1, At, B1); PG8_BAR; PG8_SCHED;
	v_mfma_f32_16x16x32_bf16 v[62:65], v[90:93], v[162:165], v[62:65]
	v_mfma_f32_16x16x32_bf16 v[62:65], v[102:105], v[166:169], v[62:65]
	v_mfma_f32_16x16x32_bf16 v[58:61], v[114:117], v[162:165], v[58:61]
	v_mfma_f32_16x16x32_bf16 v[58:61], v[126:129], v[166:169], v[58:61]
	v_mfma_f32_16x16x32_bf16 v[42:45], v[114:117], v[170:173], v[42:45]
	v_mfma_f32_16x16x32_bf16 v[42:45], v[126:129], v[174:177], v[42:45]
	v_mfma_f32_16x16x32_bf16 v[46:49], v[90:93], v[170:173], v[46:49]
	v_mfma_f32_16x16x32_bf16 v[46:49], v[102:105], v[174:177], v[46:49]
	v_mfma_f32_16x16x32_bf16 v[30:33], v[90:93], v[178:181], v[30:33]
	v_mfma_f32_16x16x32_bf16 v[30:33], v[102:105], v[182:185], v[30:33]
	v_mfma_f32_16x16x32_bf16 v[26:29], v[114:117], v[178:181], v[26:29]
	v_mfma_f32_16x16x32_bf16 v[26:29], v[126:129], v[182:185], v[26:29]
	v_mfma_f32_16x16x32_bf16 v[10:13], v[114:117], v[204:207], v[10:13]
	v_mfma_f32_16x16x32_bf16 v[10:13], v[126:129], v[208:211], v[10:13]
	v_mfma_f32_16x16x32_bf16 v[14:17], v[90:93], v[204:207], v[14:17]
	v_mfma_f32_16x16x32_bf16 v[14:17], v[102:105], v[208:211], v[14:17]
	v_mfma_f32_16x16x32_bf16 v[54:57], v[138:141], v[162:165], v[54:57]
	v_mfma_f32_16x16x32_bf16 v[54:57], v[142:145], v[166:169], v[54:57]
	v_mfma_f32_16x16x32_bf16 v[50:53], v[154:157], v[162:165], v[50:53]
	v_mfma_f32_16x16x32_bf16 v[50:53], v[158:161], v[166:169], v[50:53]
	v_mfma_f32_16x16x32_bf16 v[34:37], v[154:157], v[170:173], v[34:37]
	v_mfma_f32_16x16x32_bf16 v[34:37], v[158:161], v[174:177], v[34:37]
	v_mfma_f32_16x16x32_bf16 v[38:41], v[138:141], v[170:173], v[38:41]
	v_mfma_f32_16x16x32_bf16 v[38:41], v[142:145], v[174:177], v[38:41]
	v_mfma_f32_16x16x32_bf16 v[22:25], v[138:141], v[178:181], v[22:25]
	v_mfma_f32_16x16x32_bf16 v[22:25], v[142:145], v[182:185], v[22:25]
	v_mfma_f32_16x16x32_bf16 v[18:21], v[154:157], v[178:181], v[18:21]
	v_mfma_f32_16x16x32_bf16 v[18:21], v[158:161], v[182:185], v[18:21]
	v_mfma_f32_16x16x32_bf16 v[2:5], v[154:157], v[204:207], v[2:5]
	v_mfma_f32_16x16x32_bf16 v[2:5], v[158:161], v[208:211], v[2:5]
	v_mfma_f32_16x16x32_bf16 v[6:9], v[138:141], v[204:207], v[6:9]
	v_mfma_f32_16x16x32_bf16 v[6:9], v[142:145], v[208:211], v[6:9]
	s_barrier
	s_add_i32 s50, 0, 0x18000
	s_add_i32 s51, 0, 0x1c000
	v_add_u32_e32 v126, s50, v247
	v_add_u32_e32 v158, s51, v247
	ds_read_b128 v[90:93], v126
	ds_read_b128 v[102:105], v126 offset:1024
	ds_read_b128 v[114:117], v126 offset:2048
	ds_read_b128 v[126:129], v126 offset:3072
	ds_read_b128 v[138:141], v158
	ds_read_b128 v[142:145], v158 offset:1024
	ds_read_b128 v[154:157], v158 offset:2048
	ds_read_b128 v[158:161], v158 offset:3072
	s_add_u32 s22, s28, 0x160000
	s_addc_u32 s23, s29, 0
	s_mov_b32 m0, s8
	v_lshl_add_u64 v[212:213], s[22:23], 0, v[198:199]
	ds_read_b128 v[162:165], v249 offset:32768
	ds_read_b128 v[166:169], v249 offset:33792
	ds_read_b128 v[170:173], v249 offset:34816
	ds_read_b128 v[174:177], v249 offset:35840
	ds_read_b128 v[178:181], v249 offset:36864
	ds_read_b128 v[182:185], v249 offset:37888
	ds_read_b128 v[204:207], v249 offset:38912
	ds_read_b128 v[208:211], v249 offset:39936
	global_load_lds_dwordx4 v[212:213], off
	v_lshl_add_u64 v[212:213], s[22:23], 0, v[196:197]
	s_mov_b32 m0, s31
	s_nop 0
	global_load_lds_dwordx4 v[212:213], off
	s_waitcnt vmcnt(8)
	s_waitcnt lgkmcnt(0)
	s_barrier
	v_mfma_f32_16x16x32_bf16 v[150:153], v[90:93], v[162:165], v[150:153]
	v_mfma_f32_16x16x32_bf16 v[150:153], v[102:105], v[166:169], v[150:153]
	v_mfma_f32_16x16x32_bf16 v[146:149], v[114:117], v[162:165], v[146:149]
	v_mfma_f32_16x16x32_bf16 v[146:149], v[126:129], v[166:169], v[146:149]
	v_mfma_f32_16x16x32_bf16 v[118:121], v[114:117], v[170:173], v[118:121]
	v_mfma_f32_16x16x32_bf16 v[118:121], v[126:129], v[174:177], v[118:121]
	v_mfma_f32_16x16x32_bf16 v[122:125], v[90:93], v[170:173], v[122:125]
	v_mfma_f32_16x16x32_bf16 v[122:125], v[102:105], v[174:177], v[122:125]
	v_mfma_f32_16x16x32_bf16 v[98:101], v[90:93], v[178:181], v[98:101]
	v_mfma_f32_16x16x32_bf16 v[98:101], v[102:105], v[182:185], v[98:101]
	v_mfma_f32_16x16x32_bf16 v[94:97], v[114:117], v[178:181], v[94:97]
	v_mfma_f32_16x16x32_bf16 v[94:97], v[126:129], v[182:185], v[94:97]
	v_mfma_f32_16x16x32_bf16 v[74:77], v[114:117], v[204:207], v[74:77]
	v_mfma_f32_16x16x32_bf16 v[74:77], v[126:129], v[208:211], v[74:77]
	v_mfma_f32_16x16x32_bf16 v[78:81], v[90:93], v[204:207], v[78:81]
	v_mfma_f32_16x16x32_bf16 v[78:81], v[102:105], v[208:211], v[78:81]
	v_mfma_f32_16x16x32_bf16 v[134:137], v[138:141], v[162:165], v[134:137]
	v_mfma_f32_16x16x32_bf16 v[134:137], v[142:145], v[166:169], v[134:137]
	v_mfma_f32_16x16x32_bf16 v[130:133], v[154:157], v[162:165], v[130:133]
	v_mfma_f32_16x16x32_bf16 v[130:133], v[158:161], v[166:169], v[130:133]
	v_mfma_f32_16x16x32_bf16 v[106:109], v[154:157], v[170:173], v[106:109]
	v_mfma_f32_16x16x32_bf16 v[106:109], v[158:161], v[174:177], v[106:109]
	v_mfma_f32_16x16x32_bf16 v[110:113], v[138:141], v[170:173], v[110:113]
	v_mfma_f32_16x16x32_bf16 v[110:113], v[142:145], v[174:177], v[110:113]
	v_mfma_f32_16x16x32_bf16 v[86:89], v[138:141], v[178:181], v[86:89]
	v_mfma_f32_16x16x32_bf16 v[86:89], v[142:145], v[182:185], v[86:89]
	v_mfma_f32_16x16x32_bf16 v[82:85], v[154:157], v[178:181], v[82:85]
	v_mfma_f32_16x16x32_bf16 v[82:85], v[158:161], v[182:185], v[82:85]
	v_mfma_f32_16x16x32_bf16 v[66:69], v[154:157], v[204:207], v[66:69]
	v_mfma_f32_16x16x32_bf16 v[66:69], v[158:161], v[208:211], v[66:69]
	v_mfma_f32_16x16x32_bf16 v[70:73], v[138:141], v[204:207], v[70:73]
	v_mfma_f32_16x16x32_bf16 v[70:73], v[142:145], v[208:211], v[70:73]
	s_barrier
; #define PG8_STAGE(bufoff, gbase, voff) do { _Pragma("unroll") for (int _i = 0; _i < 2; ++_i) \
;         __builtin_amdgcn_global_load_lds((const unsigned*)((const char*)(gbase) + (voff)[_i]), (LAS unsigned*)(lds + (bufoff) + ldsw + _i * 8192), 16, 0, 0); } while (0)
; #define PG8_LDA(dst, b, h) do { _Pragma("unroll") for (int m = 0; m < 4; ++m) _Pragma("unroll") for (int k = 0; k < 2; ++k) dst[m][k] = *(const LAS bf16x8*)(lds + PG8_SA(b, h) + aoff + m * 2048 + k * 1024); } while (0)
; #define PG8_MMA(ai, bj, At, Bt) do { __builtin_amdgcn_s_setprio(1); _Pragma("unroll") for (int m = 0; m < 4; ++m) _Pragma("unroll") for (int n = 0; n < 2; ++n) _Pragma("unroll") for (int k = 0; k < 2; ++k) \
;         acc[ai][bj][m][n] = __builtin_amdgcn_mfma_f32_16x16x32_bf16(Bt[n][k], At[m][k], acc[ai][bj][m][n], 0, 0, 0); __builtin_amdgcn_s_setprio(0); } while (0)
; #define PG8_WAIT_V(n) asm volatile("s_waitcnt vmcnt(" #n ")" ::: "memory")
; #define PG8_WAIT_L(n) asm volatile("s_waitcnt lgkmcnt(" #n ")" ::: "memory")
; #define PG8_BAR __builtin_amdgcn_s_barrier()
; #define PG8_SCHED __builtin_amdgcn_sched_barrier(0)
; template <class Epi, class Sched, bool ALIGN_EPI = false, bool SP2 = false>
; __device__ __forceinline__ void gemm_phase(LAS unsigned char* lds, const Gemm g, const Sched& S, const Epi& E) {
;     ...
;         for (int t = 0; t < nt; t += 2) {
;             const bool last = (t == nt - 2);
;             const char* a1 = cA + (size_t)(t + 1) * kstep;
;             const char* a2 = last ? nA : cA + (size_t)(t + 2) * kstep; const char* b2 = last ? nB : cB + (size_t)(t + 2) * kstep;
;             const char* a3 = a2 + kstep; const char* b3 = b2 + kstep;
;             if (last && has_next) S.a_ready(nxt);
;     ...
;             PG8_WAIT_V(8); PG8_WAIT_L(0); PG8_BAR; PG8_MMA(0, 0, At, B0); PG8_MMA(0, 1, At, B1); PG8_BAR; PG8_SCHED;
;             PG8_LDA(At, 1, 1); PG8_STAGE(PG8_SB(1, 0), b3, voffB); PG8_STAGE(PG8_SB(1, 1), b3 + hstep, voffB); PG8_STAGE(PG8_SA(1, 0), a3, voffA);
;             PG8_WAIT_V(8); PG8_WAIT_L(0); PG8_BAR; PG8_MMA(1, 0, At, B0); PG8_MMA(1, 1, At, B1); PG8_BAR; PG8_SCHED;
	s_add_i32 s22, s50, s2
	v_lshl_add_u64 v[186:187], v[186:187], 0, s[12:13]
	s_mov_b32 m0, s22
	ds_read_b128 v[162:165], v249 offset:49152
	ds_read_b128 v[166:169], v249 offset:50176
	ds_read_b128 v[170:173], v249 offset:51200
	ds_read_b128 v[174:177], v249 offset:52224
	ds_read_b128 v[178:181], v249 offset:53248
	ds_read_b128 v[182:185], v249 offset:54272
	ds_read_b128 v[204:207], v249 offset:55296
	ds_read_b128 v[208:211], v249 offset:56320
	global_load_lds_dwordx4 v[186:187], off
	s_add_i32 m0, s22, 0x2000
	s_add_u32 s22, s26, 0x160080
	v_lshl_add_u64 v[186:187], v[188:189], 0, s[12:13]
	s_addc_u32 s23, s27, 0
	s_add_i32 s26, s51, s2
	global_load_lds_dwordx4 v[186:187], off
	v_lshl_add_u64 v[186:187], s[22:23], 0, v[0:1]
	s_mov_b32 m0, s26
	s_nop 0
	global_load_lds_dwordx4 v[186:187], off
	v_lshl_add_u64 v[186:187], s[22:23], 0, v[194:195]
	s_add_i32 m0, s26, 0x2000
	s_nop 0
	global_load_lds_dwordx4 v[186:187], off
	v_lshl_add_u64 v[186:187], v[190:191], 0, s[12:13]
	s_mov_b32 m0, s35
	s_nop 0
	global_load_lds_dwordx4 v[186:187], off
	v_lshl_add_u64 v[186:187], v[192:193], 0, s[12:13]
	s_mov_b32 m0, s40
	s_nop 0
	global_load_lds_dwordx4 v[186:187], off
	s_waitcnt vmcnt(8)
	s_waitcnt lgkmcnt(0)
	s_barrier
	v_mfma_f32_16x16x32_bf16 v[62:65], v[90:93], v[162:165], v[62:65]
	v_mfma_f32_16x16x32_bf16 v[62:65], v[102:105], v[166:169], v[62:65]
	v_mfma_f32_16x16x32_bf16 v[58:61], v[114:117], v[162:165], v[58:61]
	v_mfma_f32_16x16x32_bf16 v[58:61], v[126:129], v[166:169], v[58:61]
	v_mfma_f32_16x16x32_bf16 v[42:45], v[114:117], v[170:173], v[42:45]
	v_mfma_f32_16x16x32_bf16 v[42:45], v[126:129], v[174:177], v[42:45]
	v_mfma_f32_16x16x32_bf16 v[46:49], v[90:93], v[170:173], v[46:49]
	v_mfma_f32_16x16x32_bf16 v[46:49], v[102:105], v[174:177], v[46:49]
	v_mfma_f32_16x16x32_bf16 v[30:33], v[90:93], v[178:181], v[30:33]
	v_mfma_f32_16x16x32_bf16 v[30:33], v[102:105], v[182:185], v[30:33]
	v_mfma_f32_16x16x32_bf16 v[26:29], v[114:117], v[178:181], v[26:29]
	v_mfma_f32_16x16x32_bf16 v[26:29], v[126:129], v[182:185], v[26:29]
	v_mfma_f32_16x16x32_bf16 v[10:13], v[114:117], v[204:207], v[10:13]
	v_mfma_f32_16x16x32_bf16 v[10:13], v[126:129], v[208:211], v[10:13]
	v_mfma_f32_16x16x32_bf16 v[14:17], v[90:93], v[204:207], v[14:17]
	v_mfma_f32_16x16x32_bf16 v[14:17], v[102:105], v[208:211], v[14:17]
	v_mfma_f32_16x16x32_bf16 v[54:57], v[138:141], v[162:165], v[54:57]
	v_mfma_f32_16x16x32_bf16 v[54:57], v[142:145], v[166:169], v[54:57]
	v_mfma_f32_16x16x32_bf16 v[50:53], v[154:157], v[162:165], v[50:53]
	v_mfma_f32_16x16x32_bf16 v[50:53], v[158:161], v[166:169], v[50:53]
	v_mfma_f32_16x16x32_bf16 v[34:37], v[154:157], v[170:173], v[34:37]
	v_mfma_f32_16x16x32_bf16 v[34:37], v[158:161], v[174:177], v[34:37]
	v_mfma_f32_16x16x32_bf16 v[38:41], v[138:141], v[170:173], v[38:41]
	v_mfma_f32_16x16x32_bf16 v[38:41], v[142:145], v[174:177], v[38:41]
	v_mfma_f32_16x16x32_bf16 v[22:25], v[138:141], v[178:181], v[22:25]
	v_mfma_f32_16x16x32_bf16 v[22:25], v[142:145], v[182:185], v[22:25]
	v_mfma_f32_16x16x32_bf16 v[18:21], v[154:157], v[178:181], v[18:21]
	v_mfma_f32_16x16x32_bf16 v[18:21], v[158:161], v[182:185], v[18:21]
	v_mfma_f32_16x16x32_bf16 v[2:5], v[154:157], v[204:207], v[2:5]
	v_mfma_f32_16x16x32_bf16 v[2:5], v[158:161], v[208:211], v[2:5]
	v_mfma_f32_16x16x32_bf16 v[6:9], v[138:141], v[204:207], v[6:9]
	v_mfma_f32_16x16x32_bf16 v[6:9], v[142:145], v[208:211], v[6:9]
	s_barrier
	s_add_i32 s49, s49, 2
	s_add_u32 s47, s47, 0x100
	s_addc_u32 s48, s48, 0
	s_cmpk_gt_u32 s49, 0x55
	s_mov_b64 s[22:23], s[24:25]
	s_cbranch_scc0 .LBB0_257
	s_and_b64 vcc, exec, s[18:19]
	s_cbranch_vccz .LBB0_260
	s_barrier

; #define PG8_STAGE(bufoff, gbase, voff) do { _Pragma("unroll") for (int _i = 0; _i < 2; ++_i) \
;         __builtin_amdgcn_global_load_lds((const unsigned*)((const char*)(gbase) + (voff)[_i]), (LAS unsigned*)(lds + (bufoff) + ldsw + _i * 8192), 16, 0, 0); } while (0)
; #define PG8_LDA(dst, b, h) do { _Pragma("unroll") for (int m = 0; m < 4; ++m) _Pragma("unroll") for (int k = 0; k < 2; ++k) dst[m][k] = *(const LAS bf16x8*)(lds + PG8_SA(b, h) + aoff + m * 2048 + k * 1024); } while (0)
; #define PG8_LDB(dst, b, h) do { _Pragma("unroll") for (int n = 0; n < 2; ++n) _Pragma("unroll") for (int k = 0; k < 2; ++k) dst[n][k] = *(const LAS bf16x8*)(lds + PG8_SB(b, h) + boff + n * 2048 + k * 1024); } while (0)
; #define PG8_MMA(ai, bj, At, Bt) do { __builtin_amdgcn_s_setprio(1); _Pragma("unroll") for (int m = 0; m < 4; ++m) _Pragma("unroll") for (int n = 0; n < 2; ++n) _Pragma("unroll") for (int k = 0; k < 2; ++k) \
;         acc[ai][bj][m][n] = __builtin_amdgcn_mfma_f32_16x16x32_bf16(Bt[n][k], At[m][k], acc[ai][bj][m][n], 0, 0, 0); __builtin_amdgcn_s_setprio(0); } while (0)
; #define PG8_WAIT_V(n) asm volatile("s_waitcnt vmcnt(" #n ")" ::: "memory")
; #define PG8_WAIT_L(n) asm volatile("s_waitcnt lgkmcnt(" #n ")" ::: "memory")
; template <class Epi, class Sched, bool ALIGN_EPI = false, bool SP2 = false>
; __device__ __forceinline__ void gemm_phase(LAS unsigned char* lds, const Gemm g, const Sched& S, const Epi& E) {
;     ...
;         for (int t = 0; t < nt; t += 2) {
;             const bool last = (t == nt - 2);
;             const char* a1 = cA + (size_t)(t + 1) * kstep;
;             const char* a2 = last ? nA : cA + (size_t)(t + 2) * kstep; const char* b2 = last ? nB : cB + (size_t)(t + 2) * kstep;
;             const char* a3 = a2 + kstep; const char* b3 = b2 + kstep;
;             if (last && has_next) S.a_ready(nxt);
;             if constexpr (SP2) {
;             PG8_LDB(B0, 0, 0); PG8_LDB(B1, 0, 1); PG8_SCHED; PG8_LDA(At, 0, 0); PG8_STAGE(PG8_SA(1, 1), a1 + hstep, voffA);
;             PG8_WAIT_V(8); PG8_WAIT_L(0); PG8_BAR; PG8_MMA(0, 0, At, B0); PG8_MMA(0, 1, At, B1); PG8_BAR; PG8_SCHED;
;             PG8_LDA(At, 0, 1); PG8_STAGE(PG8_SB(0, 0), b2, voffB); PG8_STAGE(PG8_SB(0, 1), b2 + hstep, voffB); PG8_STAGE(PG8_SA(0, 0), a2, voffA);
;             PG8_WAIT_V(8); PG8_WAIT_L(0); PG8_BAR; PG8_MMA(1, 0, At, B0); PG8_MMA(1, 1, At, B1); PG8_BAR; PG8_SCHED;
.LBB0_359:
	s_add_u32 s28, s26, 0xfff80080
	s_addc_u32 s29, s27, -1
	s_add_i32 s41, 0, 0x10000
	s_cmp_eq_u32 s40, 28
	s_cselect_b32 s31, s6, s29
	s_cselect_b32 s30, s7, s28
	v_add_u32_e32 v0, s41, v159
	s_cselect_b32 s29, s8, s35
	s_cselect_b32 s28, s19, s21
	s_add_i32 s57, 0, 0x14000
	ds_read_b128 v[142:145], v0
	ds_read_b128 v[146:149], v0 offset:1024
	ds_read_b128 v[150:153], v0 offset:2048
	ds_read_b128 v[154:157], v0 offset:3072
	v_add_u32_e32 v0, s57, v159
	ds_read_b128 v[162:165], v0
	ds_read_b128 v[166:169], v0 offset:1024
	ds_read_b128 v[170:173], v0 offset:2048
	ds_read_b128 v[174:177], v0 offset:3072
	v_lshl_add_u64 v[210:211], s[26:27], 0, v[138:139]
	s_add_i32 m0, s44, 0xc000
	ds_read_b128 v[178:181], v161
	ds_read_b128 v[182:185], v161 offset:1024
	ds_read_b128 v[186:189], v161 offset:2048
	ds_read_b128 v[190:193], v161 offset:3072
	ds_read_b128 v[194:197], v161 offset:4096
	ds_read_b128 v[198:201], v161 offset:5120
	ds_read_b128 v[202:205], v161 offset:6144
	ds_read_b128 v[206:209], v161 offset:7168
	global_load_lds_dwordx4 v[210:211], off
	v_lshl_add_u64 v[210:211], s[26:27], 0, v[140:141]
	s_add_i32 m0, s44, 0xe000
	s_nop 0
	global_load_lds_dwordx4 v[210:211], off
	s_waitcnt vmcnt(8)
	s_waitcnt lgkmcnt(0)
	s_barrier
	v_mfma_f32_16x16x32_bf16 v[126:129], v[142:145], v[178:181], v[126:129]
	v_mfma_f32_16x16x32_bf16 v[126:129], v[146:149], v[182:185], v[126:129]
	v_mfma_f32_16x16x32_bf16 v[122:125], v[150:153], v[178:181], v[122:125]
	v_mfma_f32_16x16x32_bf16 v[122:125], v[154:157], v[182:185], v[122:125]
	v_mfma_f32_16x16x32_bf16 v[106:109], v[150:153], v[186:189], v[106:109]
	v_mfma_f32_16x16x32_bf16 v[106:109], v[154:157], v[190:193], v[106:109]
	v_mfma_f32_16x16x32_bf16 v[110:113], v[142:145], v[186:189], v[110:113]
	v_mfma_f32_16x16x32_bf16 v[110:113], v[146:149], v[190:193], v[110:113]
	v_mfma_f32_16x16x32_bf16 v[94:97], v[142:145], v[194:197], v[94:97]
	v_mfma_f32_16x16x32_bf16 v[94:97], v[146:149], v[198:201], v[94:97]
	v_mfma_f32_16x16x32_bf16 v[90:93], v[150:153], v[194:197], v[90:93]
	v_mfma_f32_16x16x32_bf16 v[90:93], v[154:157], v[198:201], v[90:93]
	v_mfma_f32_16x16x32_bf16 v[74:77], v[150:153], v[202:205], v[74:77]
	v_mfma_f32_16x16x32_bf16 v[74:77], v[154:157], v[206:209], v[74:77]
	v_mfma_f32_16x16x32_bf16 v[78:81], v[142:145], v[202:205], v[78:81]
	v_mfma_f32_16x16x32_bf16 v[78:81], v[146:149], v[206:209], v[78:81]
	v_mfma_f32_16x16x32_bf16 v[118:121], v[162:165], v[178:181], v[118:121]
	v_mfma_f32_16x16x32_bf16 v[118:121], v[166:169], v[182:185], v[118:121]
	v_mfma_f32_16x16x32_bf16 v[114:117], v[170:173], v[178:181], v[114:117]
	v_mfma_f32_16x16x32_bf16 v[114:117], v[174:177], v[182:185], v[114:117]
	v_mfma_f32_16x16x32_bf16 v[98:101], v[170:173], v[186:189], v[98:101]
	v_mfma_f32_16x16x32_bf16 v[98:101], v[174:177], v[190:193], v[98:101]
	v_mfma_f32_16x16x32_bf16 v[102:105], v[162:165], v[186:189], v[102:105]
	v_mfma_f32_16x16x32_bf16 v[102:105], v[166:169], v[190:193], v[102:105]
	v_mfma_f32_16x16x32_bf16 v[86:89], v[162:165], v[194:197], v[86:89]
	v_mfma_f32_16x16x32_bf16 v[86:89], v[166:169], v[198:201], v[86:89]
	v_mfma_f32_16x16x32_bf16 v[82:85], v[170:173], v[194:197], v[82:85]
	v_mfma_f32_16x16x32_bf16 v[82:85], v[174:177], v[198:201], v[82:85]
	v_mfma_f32_16x16x32_bf16 v[66:69], v[170:173], v[202:205], v[66:69]
	v_mfma_f32_16x16x32_bf16 v[66:69], v[174:177], v[206:209], v[66:69]
	v_mfma_f32_16x16x32_bf16 v[70:73], v[162:165], v[202:205], v[70:73]
	v_mfma_f32_16x16x32_bf16 v[70:73], v[166:169], v[206:209], v[70:73]
	s_barrier
	s_add_i32 s41, s41, s9
	v_lshl_add_u64 v[210:211], s[28:29], 0, v[134:135]
	s_mov_b32 m0, s41
	ds_read_b128 v[178:181], v161 offset:16384
	ds_read_b128 v[182:185], v161 offset:17408
	ds_read_b128 v[186:189], v161 offset:18432
	ds_read_b128 v[190:193], v161 offset:19456
	ds_read_b128 v[194:197], v161 offset:20480
	ds_read_b128 v[198:201], v161 offset:21504
	ds_read_b128 v[202:205], v161 offset:22528
	ds_read_b128 v[206:209], v161 offset:23552
	global_load_lds_dwordx4 v[210:211], off
	s_add_i32 m0, s41, 0x2000
	s_add_u32 s58, s28, 0x80000
	v_lshl_add_u64 v[212:213], s[28:29], 0, v[130:131]
	s_addc_u32 s59, s29, 0
	s_add_i32 s41, s57, s9
	global_load_lds_dwordx4 v[212:213], off
	v_lshl_add_u64 v[214:215], s[58:59], 0, v[134:135]
	s_mov_b32 m0, s41
	v_lshl_add_u64 v[216:217], s[30:31], 0, v[132:133]
	global_load_lds_dwordx4 v[214:215], off
	v_lshl_add_u64 v[214:215], s[58:59], 0, v[130:131]
	s_add_i32 m0, s41, 0x2000
	s_nop 0
	global_load_lds_dwordx4 v[214:215], off
	v_lshl_add_u64 v[214:215], s[30:31], 0, v[136:137]
	s_mov_b32 m0, s44
	s_nop 0
	global_load_lds_dwordx4 v[214:215], off
	s_mov_b32 m0, s45
	s_nop 0
	global_load_lds_dwordx4 v[216:217], off
	s_waitcnt vmcnt(8)
	s_waitcnt lgkmcnt(0)
	s_barrier
; #define PG8_STAGE(bufoff, gbase, voff) do { _Pragma("unroll") for (int _i = 0; _i < 2; ++_i) \
;         __builtin_amdgcn_global_load_lds((const unsigned*)((const char*)(gbase) + (voff)[_i]), (LAS unsigned*)(lds + (bufoff) + ldsw + _i * 8192), 16, 0, 0); } while (0)
; #define PG8_LDA(dst, b, h) do { _Pragma("unroll") for (int m = 0; m < 4; ++m) _Pragma("unroll") for (int k = 0; k < 2; ++k) dst[m][k] = *(const LAS bf16x8*)(lds + PG8_SA(b, h) + aoff + m * 2048 + k * 1024); } while (0)
; #define PG8_LDB(dst, b, h) do { _Pragma("unroll") for (int n = 0; n < 2; ++n) _Pragma("unroll") for (int k = 0; k < 2; ++k) dst[n][k] = *(const LAS bf16x8*)(lds + PG8_SB(b, h) + boff + n * 2048 + k * 1024); } while (0)
; #define PG8_MMA(ai, bj, At, Bt) do { __builtin_amdgcn_s_setprio(1); _Pragma("unroll") for (int m = 0; m < 4; ++m) _Pragma("unroll") for (int n = 0; n < 2; ++n) _Pragma("unroll") for (int k = 0; k < 2; ++k) \
;         acc[ai][bj][m][n] = __builtin_amdgcn_mfma_f32_16x16x32_bf16(Bt[n][k], At[m][k], acc[ai][bj][m][n], 0, 0, 0); __builtin_amdgcn_s_setprio(0); } while (0)
; #define PG8_WAIT_V(n) asm volatile("s_waitcnt vmcnt(" #n ")" ::: "memory")
; #define PG8_WAIT_L(n) asm volatile("s_waitcnt lgkmcnt(" #n ")" ::: "memory")
; #define PG8_BAR __builtin_amdgcn_s_barrier()
; #define PG8_SCHED __builtin_amdgcn_sched_barrier(0)
; template <class Epi, class Sched, bool ALIGN_EPI = false, bool SP2 = false>
; __device__ __forceinline__ void gemm_phase(LAS unsigned char* lds, const Gemm g, const Sched& S, const Epi& E) {
;     ...
;             PG8_WAIT_V(8); PG8_WAIT_L(0); PG8_BAR; PG8_MMA(1, 0, At, B0); PG8_MMA(1, 1, At, B1); PG8_BAR; PG8_SCHED;
;             PG8_LDB(B0, 1, 0); PG8_LDB(B1, 1, 1); PG8_SCHED; PG8_LDA(At, 1, 0); PG8_STAGE(PG8_SA(0, 1), a2 + hstep, voffA);
;             PG8_WAIT_V(8); PG8_WAIT_L(0); PG8_BAR; PG8_MMA(0, 0, At, B0); PG8_MMA(0, 1, At, B1); PG8_BAR; PG8_SCHED;
	v_mfma_f32_16x16x32_bf16 v[62:65], v[142:145], v[178:181], v[62:65]
	v_mfma_f32_16x16x32_bf16 v[62:65], v[146:149], v[182:185], v[62:65]
	v_mfma_f32_16x16x32_bf16 v[58:61], v[150:153], v[178:181], v[58:61]
	v_mfma_f32_16x16x32_bf16 v[58:61], v[154:157], v[182:185], v[58:61]
	v_mfma_f32_16x16x32_bf16 v[42:45], v[150:153], v[186:189], v[42:45]
	v_mfma_f32_16x16x32_bf16 v[42:45], v[154:157], v[190:193], v[42:45]
	v_mfma_f32_16x16x32_bf16 v[46:49], v[142:145], v[186:189], v[46:49]
	v_mfma_f32_16x16x32_bf16 v[46:49], v[146:149], v[190:193], v[46:49]
	v_mfma_f32_16x16x32_bf16 v[30:33], v[142:145], v[194:197], v[30:33]
	v_mfma_f32_16x16x32_bf16 v[30:33], v[146:149], v[198:201], v[30:33]
	v_mfma_f32_16x16x32_bf16 v[26:29], v[150:153], v[194:197], v[26:29]
	v_mfma_f32_16x16x32_bf16 v[26:29], v[154:157], v[198:201], v[26:29]
	v_mfma_f32_16x16x32_bf16 v[10:13], v[150:153], v[202:205], v[10:13]
	v_mfma_f32_16x16x32_bf16 v[10:13], v[154:157], v[206:209], v[10:13]
	v_mfma_f32_16x16x32_bf16 v[14:17], v[142:145], v[202:205], v[14:17]
	v_mfma_f32_16x16x32_bf16 v[14:17], v[146:149], v[206:209], v[14:17]
	v_mfma_f32_16x16x32_bf16 v[54:57], v[162:165], v[178:181], v[54:57]
	v_mfma_f32_16x16x32_bf16 v[54:57], v[166:169], v[182:185], v[54:57]
	v_mfma_f32_16x16x32_bf16 v[50:53], v[170:173], v[178:181], v[50:53]
	v_mfma_f32_16x16x32_bf16 v[50:53], v[174:177], v[182:185], v[50:53]
	v_mfma_f32_16x16x32_bf16 v[34:37], v[170:173], v[186:189], v[34:37]
	v_mfma_f32_16x16x32_bf16 v[34:37], v[174:177], v[190:193], v[34:37]
	v_mfma_f32_16x16x32_bf16 v[38:41], v[162:165], v[186:189], v[38:41]
	v_mfma_f32_16x16x32_bf16 v[38:41], v[166:169], v[190:193], v[38:41]
	v_mfma_f32_16x16x32_bf16 v[22:25], v[162:165], v[194:197], v[22:25]
	v_mfma_f32_16x16x32_bf16 v[22:25], v[166:169], v[198:201], v[22:25]
	v_mfma_f32_16x16x32_bf16 v[18:21], v[170:173], v[194:197], v[18:21]
	v_mfma_f32_16x16x32_bf16 v[18:21], v[174:177], v[198:201], v[18:21]
	v_mfma_f32_16x16x32_bf16 v[2:5], v[170:173], v[202:205], v[2:5]
	v_mfma_f32_16x16x32_bf16 v[2:5], v[174:177], v[206:209], v[2:5]
	v_mfma_f32_16x16x32_bf16 v[6:9], v[162:165], v[202:205], v[6:9]
	v_mfma_f32_16x16x32_bf16 v[6:9], v[166:169], v[206:209], v[6:9]
	s_barrier
	s_add_i32 s41, 0, 0x18000
	v_add_u32_e32 v0, s41, v159
	s_add_i32 s57, 0, 0x1c000
	ds_read_b128 v[142:145], v0
	ds_read_b128 v[146:149], v0 offset:1024
	ds_read_b128 v[150:153], v0 offset:2048
	ds_read_b128 v[154:157], v0 offset:3072
	v_add_u32_e32 v0, s57, v159
	ds_read_b128 v[162:165], v0
	ds_read_b128 v[166:169], v0 offset:1024
	ds_read_b128 v[170:173], v0 offset:2048
	ds_read_b128 v[174:177], v0 offset:3072
	s_add_u32 s30, s30, 0x80000
	s_addc_u32 s31, s31, 0
	s_mov_b32 m0, s47
	v_lshl_add_u64 v[218:219], s[30:31], 0, v[136:137]
	ds_read_b128 v[178:181], v161 offset:32768
	ds_read_b128 v[182:185], v161 offset:33792
	ds_read_b128 v[186:189], v161 offset:34816
	ds_read_b128 v[190:193], v161 offset:35840
	ds_read_b128 v[194:197], v161 offset:36864
	ds_read_b128 v[198:201], v161 offset:37888
	ds_read_b128 v[202:205], v161 offset:38912
	ds_read_b128 v[206:209], v161 offset:39936
	global_load_lds_dwordx4 v[218:219], off
	v_lshl_add_u64 v[218:219], s[30:31], 0, v[132:133]
	s_mov_b32 m0, s48
	s_nop 0
	global_load_lds_dwordx4 v[218:219], off
	s_waitcnt vmcnt(8)
	s_waitcnt lgkmcnt(0)
	s_barrier
	v_mfma_f32_16x16x32_bf16 v[126:129], v[142:145], v[178:181], v[126:129]
	v_mfma_f32_16x16x32_bf16 v[126:129], v[146:149], v[182:185], v[126:129]
	v_mfma_f32_16x16x32_bf16 v[122:125], v[150:153], v[178:181], v[122:125]
	v_mfma_f32_16x16x32_bf16 v[122:125], v[154:157], v[182:185], v[122:125]
	v_mfma_f32_16x16x32_bf16 v[106:109], v[150:153], v[186:189], v[106:109]
	v_mfma_f32_16x16x32_bf16 v[106:109], v[154:157], v[190:193], v[106:109]
	v_mfma_f32_16x16x32_bf16 v[110:113], v[142:145], v[186:189], v[110:113]
	v_mfma_f32_16x16x32_bf16 v[110:113], v[146:149], v[190:193], v[110:113]
	v_mfma_f32_16x16x32_bf16 v[94:97], v[142:145], v[194:197], v[94:97]
	v_mfma_f32_16x16x32_bf16 v[94:97], v[146:149], v[198:201], v[94:97]
	v_mfma_f32_16x16x32_bf16 v[90:93], v[150:153], v[194:197], v[90:93]
	v_mfma_f32_16x16x32_bf16 v[90:93], v[154:157], v[198:201], v[90:93]
	v_mfma_f32_16x16x32_bf16 v[74:77], v[150:153], v[202:205], v[74:77]
	v_mfma_f32_16x16x32_bf16 v[74:77], v[154:157], v[206:209], v[74:77]
	v_mfma_f32_16x16x32_bf16 v[78:81], v[142:145], v[202:205], v[78:81]
	v_mfma_f32_16x16x32_bf16 v[78:81], v[146:149], v[206:209], v[78:81]
	v_mfma_f32_16x16x32_bf16 v[118:121], v[162:165], v[178:181], v[118:121]
	v_mfma_f32_16x16x32_bf16 v[118:121], v[166:169], v[182:185], v[118:121]
	v_mfma_f32_16x16x32_bf16 v[114:117], v[170:173], v[178:181], v[114:117]
	v_mfma_f32_16x16x32_bf16 v[114:117], v[174:177], v[182:185], v[114:117]
	v_mfma_f32_16x16x32_bf16 v[98:101], v[170:173], v[186:189], v[98:101]
	v_mfma_f32_16x16x32_bf16 v[98:101], v[174:177], v[190:193], v[98:101]
	v_mfma_f32_16x16x32_bf16 v[102:105], v[162:165], v[186:189], v[102:105]
	v_mfma_f32_16x16x32_bf16 v[102:105], v[166:169], v[190:193], v[102:105]
	v_mfma_f32_16x16x32_bf16 v[86:89], v[162:165], v[194:197], v[86:89]
	v_mfma_f32_16x16x32_bf16 v[86:89], v[166:169], v[198:201], v[86:89]
	v_mfma_f32_16x16x32_bf16 v[82:85], v[170:173], v[194:197], v[82:85]
	v_mfma_f32_16x16x32_bf16 v[82:85], v[174:177], v[198:201], v[82:85]
	v_mfma_f32_16x16x32_bf16 v[66:69], v[170:173], v[202:205], v[66:69]
	v_mfma_f32_16x16x32_bf16 v[66:69], v[174:177], v[206:209], v[66:69]
	v_mfma_f32_16x16x32_bf16 v[70:73], v[162:165], v[202:205], v[70:73]
	v_mfma_f32_16x16x32_bf16 v[70:73], v[166:169], v[206:209], v[70:73]
	s_barrier
; #define PG8_STAGE(bufoff, gbase, voff) do { _Pragma("unroll") for (int _i = 0; _i < 2; ++_i) \
;         __builtin_amdgcn_global_load_lds((const unsigned*)((const char*)(gbase) + (voff)[_i]), (LAS unsigned*)(lds + (bufoff) + ldsw + _i * 8192), 16, 0, 0); } while (0)
; #define PG8_LDA(dst, b, h) do { _Pragma("unroll") for (int m = 0; m < 4; ++m) _Pragma("unroll") for (int k = 0; k < 2; ++k) dst[m][k] = *(const LAS bf16x8*)(lds + PG8_SA(b, h) + aoff + m * 2048 + k * 1024); } while (0)
; #define PG8_MMA(ai, bj, At, Bt) do { __builtin_amdgcn_s_setprio(1); _Pragma("unroll") for (int m = 0; m < 4; ++m) _Pragma("unroll") for (int n = 0; n < 2; ++n) _Pragma("unroll") for (int k = 0; k < 2; ++k) \
;         acc[ai][bj][m][n] = __builtin_amdgcn_mfma_f32_16x16x32_bf16(Bt[n][k], At[m][k], acc[ai][bj][m][n], 0, 0, 0); __builtin_amdgcn_s_setprio(0); } while (0)
; #define PG8_WAIT_V(n) asm volatile("s_waitcnt vmcnt(" #n ")" ::: "memory")
; #define PG8_WAIT_L(n) asm volatile("s_waitcnt lgkmcnt(" #n ")" ::: "memory")
; #define PG8_BAR __builtin_amdgcn_s_barrier()
; #define PG8_SCHED __builtin_amdgcn_sched_barrier(0)
; template <class Epi, class Sched, bool ALIGN_EPI = false, bool SP2 = false>
; __device__ __forceinline__ void gemm_phase(LAS unsigned char* lds, const Gemm g, const Sched& S, const Epi& E) {
;     ...
;         for (int t = 0; t < nt; t += 2) {
;             const bool last = (t == nt - 2);
;             const char* a1 = cA + (size_t)(t + 1) * kstep;
;             const char* a2 = last ? nA : cA + (size_t)(t + 2) * kstep; const char* b2 = last ? nB : cB + (size_t)(t + 2) * kstep;
;             const char* a3 = a2 + kstep; const char* b3 = b2 + kstep;
;             if (last && has_next) S.a_ready(nxt);
;     ...
;             PG8_WAIT_V(8); PG8_WAIT_L(0); PG8_BAR; PG8_MMA(0, 0, At, B0); PG8_MMA(0, 1, At, B1); PG8_BAR; PG8_SCHED;
;             PG8_LDA(At, 1, 1); PG8_STAGE(PG8_SB(1, 0), b3, voffB); PG8_STAGE(PG8_SB(1, 1), b3 + hstep, voffB); PG8_STAGE(PG8_SA(1, 0), a3, voffA);
;             PG8_WAIT_V(8); PG8_WAIT_L(0); PG8_BAR; PG8_MMA(1, 0, At, B0); PG8_MMA(1, 1, At, B1); PG8_BAR; PG8_SCHED;
	s_add_i32 s30, s41, s9
	v_lshl_add_u64 v[210:211], v[210:211], 0, s[12:13]
	s_mov_b32 m0, s30
	ds_read_b128 v[178:181], v161 offset:49152
	ds_read_b128 v[182:185], v161 offset:50176
	ds_read_b128 v[186:189], v161 offset:51200
	ds_read_b128 v[190:193], v161 offset:52224
	ds_read_b128 v[194:197], v161 offset:53248
	ds_read_b128 v[198:201], v161 offset:54272
	ds_read_b128 v[202:205], v161 offset:55296
	ds_read_b128 v[206:209], v161 offset:56320
	global_load_lds_dwordx4 v[210:211], off
	s_add_i32 m0, s30, 0x2000
	s_add_u32 s28, s28, 0x80080
	v_lshl_add_u64 v[210:211], v[212:213], 0, s[12:13]
	s_addc_u32 s29, s29, 0
	s_add_i32 s30, s57, s9
	global_load_lds_dwordx4 v[210:211], off
	v_lshl_add_u64 v[210:211], s[28:29], 0, v[134:135]
	s_mov_b32 m0, s30
	s_nop 0
	global_load_lds_dwordx4 v[210:211], off
	v_lshl_add_u64 v[210:211], s[28:29], 0, v[130:131]
	s_add_i32 m0, s30, 0x2000
	s_nop 0
	global_load_lds_dwordx4 v[210:211], off
	v_lshl_add_u64 v[210:211], v[214:215], 0, s[12:13]
	s_mov_b32 m0, s53
	s_nop 0
	global_load_lds_dwordx4 v[210:211], off
	v_lshl_add_u64 v[210:211], v[216:217], 0, s[12:13]
	s_mov_b32 m0, s54
	s_nop 0
	global_load_lds_dwordx4 v[210:211], off
	s_waitcnt vmcnt(8)
	s_waitcnt lgkmcnt(0)
	s_barrier
	v_mfma_f32_16x16x32_bf16 v[62:65], v[142:145], v[178:181], v[62:65]
	v_mfma_f32_16x16x32_bf16 v[62:65], v[146:149], v[182:185], v[62:65]
	v_mfma_f32_16x16x32_bf16 v[58:61], v[150:153], v[178:181], v[58:61]
	v_mfma_f32_16x16x32_bf16 v[58:61], v[154:157], v[182:185], v[58:61]
	v_mfma_f32_16x16x32_bf16 v[42:45], v[150:153], v[186:189], v[42:45]
	v_mfma_f32_16x16x32_bf16 v[42:45], v[154:157], v[190:193], v[42:45]
	v_mfma_f32_16x16x32_bf16 v[46:49], v[142:145], v[186:189], v[46:49]
	v_mfma_f32_16x16x32_bf16 v[46:49], v[146:149], v[190:193], v[46:49]
	v_mfma_f32_16x16x32_bf16 v[30:33], v[142:145], v[194:197], v[30:33]
	v_mfma_f32_16x16x32_bf16 v[30:33], v[146:149], v[198:201], v[30:33]
	v_mfma_f32_16x16x32_bf16 v[26:29], v[150:153], v[194:197], v[26:29]
	v_mfma_f32_16x16x32_bf16 v[26:29], v[154:157], v[198:201], v[26:29]
	v_mfma_f32_16x16x32_bf16 v[10:13], v[150:153], v[202:205], v[10:13]
	v_mfma_f32_16x16x32_bf16 v[10:13], v[154:157], v[206:209], v[10:13]
	v_mfma_f32_16x16x32_bf16 v[14:17], v[142:145], v[202:205], v[14:17]
	v_mfma_f32_16x16x32_bf16 v[14:17], v[146:149], v[206:209], v[14:17]
	v_mfma_f32_16x16x32_bf16 v[54:57], v[162:165], v[178:181], v[54:57]
	v_mfma_f32_16x16x32_bf16 v[54:57], v[166:169], v[182:185], v[54:57]
	v_mfma_f32_16x16x32_bf16 v[50:53], v[170:173], v[178:181], v[50:53]
	v_mfma_f32_16x16x32_bf16 v[50:53], v[174:177], v[182:185], v[50:53]
	v_mfma_f32_16x16x32_bf16 v[34:37], v[170:173], v[186:189], v[34:37]
	v_mfma_f32_16x16x32_bf16 v[34:37], v[174:177], v[190:193], v[34:37]
	v_mfma_f32_16x16x32_bf16 v[38:41], v[162:165], v[186:189], v[38:41]
	v_mfma_f32_16x16x32_bf16 v[38:41], v[166:169], v[190:193], v[38:41]
	v_mfma_f32_16x16x32_bf16 v[22:25], v[162:165], v[194:197], v[22:25]
	v_mfma_f32_16x16x32_bf16 v[22:25], v[166:169], v[198:201], v[22:25]
	v_mfma_f32_16x16x32_bf16 v[18:21], v[170:173], v[194:197], v[18:21]
	v_mfma_f32_16x16x32_bf16 v[18:21], v[174:177], v[198:201], v[18:21]
	v_mfma_f32_16x16x32_bf16 v[2:5], v[170:173], v[202:205], v[2:5]
	v_mfma_f32_16x16x32_bf16 v[2:5], v[174:177], v[206:209], v[2:5]
	v_mfma_f32_16x16x32_bf16 v[6:9], v[162:165], v[202:205], v[6:9]
	v_mfma_f32_16x16x32_bf16 v[6:9], v[166:169], v[206:209], v[6:9]
	s_barrier
	s_add_i32 s40, s40, 2
	s_add_u32 s26, s26, 0x100
	s_addc_u32 s27, s27, 0
	s_add_u32 s21, s21, 0x100
	s_addc_u32 s35, s35, 0
	s_cmp_gt_u32 s40, 29
	s_cbranch_scc0 .LBB0_359
	s_and_b64 vcc, exec, s[16:17]
	s_cbranch_vccz .LBB0_362
	s_barrier

; #define PG8_STAGE(bufoff, gbase, voff) do { _Pragma("unroll") for (int _i = 0; _i < 2; ++_i) \
;         __builtin_amdgcn_global_load_lds((const unsigned*)((const char*)(gbase) + (voff)[_i]), (LAS unsigned*)(lds + (bufoff) + ldsw + _i * 8192), 16, 0, 0); } while (0)
; #define PG8_LDA(dst, b, h) do { _Pragma("unroll") for (int m = 0; m < 4; ++m) _Pragma("unroll") for (int k = 0; k < 2; ++k) dst[m][k] = *(const LAS bf16x8*)(lds + PG8_SA(b, h) + aoff + m * 2048 + k * 1024); } while (0)
; #define PG8_LDB(dst, b, h) do { _Pragma("unroll") for (int n = 0; n < 2; ++n) _Pragma("unroll") for (int k = 0; k < 2; ++k) dst[n][k] = *(const LAS bf16x8*)(lds + PG8_SB(b, h) + boff + n * 2048 + k * 1024); } while (0)
; #define PG8_MMA(ai, bj, At, Bt) do { __builtin_amdgcn_s_setprio(1); _Pragma("unroll") for (int m = 0; m < 4; ++m) _Pragma("unroll") for (int n = 0; n < 2; ++n) _Pragma("unroll") for (int k = 0; k < 2; ++k) \
;         acc[ai][bj][m][n] = __builtin_amdgcn_mfma_f32_16x16x32_bf16(Bt[n][k], At[m][k], acc[ai][bj][m][n], 0, 0, 0); __builtin_amdgcn_s_setprio(0); } while (0)
; template <class Epi, class Sched, bool ALIGN_EPI = false, bool SP2 = false>
; __device__ __forceinline__ void gemm_phase(LAS unsigned char* lds, const Gemm g, const Sched& S, const Epi& E) {
;     ...
;         const char* nA = has_next ? (const char*)g.A + (size_t)nxt.pm * tstep : cA; const char* nB = has_next ? (const char*)g.Bt + (size_t)nxt.pn * tstep : cB;
;         for (int t = 0; t < nt; t += 2) {
;             const bool last = (t == nt - 2);
;             const char* a1 = cA + (size_t)(t + 1) * kstep;
;             const char* a2 = last ? nA : cA + (size_t)(t + 2) * kstep; const char* b2 = last ? nB : cB + (size_t)(t + 2) * kstep;
;             const char* a3 = a2 + kstep; const char* b3 = b2 + kstep;
;             if (last && has_next) S.a_ready(nxt);
;             if constexpr (SP2) {
;             PG8_LDB(B0, 0, 0); PG8_LDB(B1, 0, 1); PG8_SCHED; PG8_LDA(At, 0, 0); PG8_STAGE(PG8_SA(1, 1), a1 + hstep, voffA);
;             PG8_WAIT_V(8); PG8_WAIT_L(0); PG8_BAR; PG8_MMA(0, 0, At, B0); PG8_MMA(0, 1, At, B1); PG8_BAR; PG8_SCHED;
;             PG8_LDA(At, 0, 1); PG8_STAGE(PG8_SB(0, 0), b2, voffB); PG8_STAGE(PG8_SB(0, 1), b2 + hstep, voffB); PG8_STAGE(PG8_SA(0, 0), a2, voffA);
;             PG8_WAIT_V(8); PG8_WAIT_L(0); PG8_BAR; PG8_MMA(1, 0, At, B0); PG8_MMA(1, 1, At, B1); PG8_BAR; PG8_SCHED;
.LBB0_833:
	s_add_u32 s28, s26, 0xfff80080
	s_addc_u32 s29, s27, -1
	s_add_i32 s53, 0, 0x10000
	s_cmp_eq_u32 s52, 28
	s_cselect_b32 s31, s21, s29
	s_cselect_b32 s30, s48, s28
	s_cselect_b32 s29, s19, s51
	s_cselect_b32 s28, s49, s50
	s_add_i32 s56, 0, 0x14000
	v_add_u32_e32 v134, s53, v247
	v_add_u32_e32 v158, s56, v247
	ds_read_b128 v[106:109], v134
	ds_read_b128 v[110:113], v134 offset:1024
	ds_read_b128 v[122:125], v134 offset:2048
	ds_read_b128 v[134:137], v134 offset:3072
	ds_read_b128 v[146:149], v158
	ds_read_b128 v[150:153], v158 offset:1024
	ds_read_b128 v[154:157], v158 offset:2048
	ds_read_b128 v[158:161], v158 offset:3072
	v_lshl_add_u64 v[204:205], s[26:27], 0, v[200:201]
	s_add_i32 m0, s8, 0xc000
	ds_read_b128 v[162:165], v249
	ds_read_b128 v[166:169], v249 offset:1024
	ds_read_b128 v[170:173], v249 offset:2048
	ds_read_b128 v[174:177], v249 offset:3072
	ds_read_b128 v[178:181], v249 offset:4096
	ds_read_b128 v[182:185], v249 offset:5120
	ds_read_b128 v[186:189], v249 offset:6144
	ds_read_b128 v[190:193], v249 offset:7168
	global_load_lds_dwordx4 v[204:205], off
	v_lshl_add_u64 v[204:205], s[26:27], 0, v[202:203]
	s_add_i32 m0, s8, 0xe000
	s_nop 0
	global_load_lds_dwordx4 v[204:205], off
	s_waitcnt vmcnt(8)
	s_waitcnt lgkmcnt(0)
	s_barrier
	v_mfma_f32_16x16x32_bf16 v[142:145], v[106:109], v[162:165], v[142:145]
	v_mfma_f32_16x16x32_bf16 v[142:145], v[110:113], v[166:169], v[142:145]
	v_mfma_f32_16x16x32_bf16 v[138:141], v[122:125], v[162:165], v[138:141]
	v_mfma_f32_16x16x32_bf16 v[138:141], v[134:137], v[166:169], v[138:141]
	v_mfma_f32_16x16x32_bf16 v[114:117], v[122:125], v[170:173], v[114:117]
	v_mfma_f32_16x16x32_bf16 v[114:117], v[134:137], v[174:177], v[114:117]
	v_mfma_f32_16x16x32_bf16 v[118:121], v[106:109], v[170:173], v[118:121]
	v_mfma_f32_16x16x32_bf16 v[118:121], v[110:113], v[174:177], v[118:121]
	v_mfma_f32_16x16x32_bf16 v[94:97], v[106:109], v[178:181], v[94:97]
	v_mfma_f32_16x16x32_bf16 v[94:97], v[110:113], v[182:185], v[94:97]
	v_mfma_f32_16x16x32_bf16 v[90:93], v[122:125], v[178:181], v[90:93]
	v_mfma_f32_16x16x32_bf16 v[90:93], v[134:137], v[182:185], v[90:93]
	v_mfma_f32_16x16x32_bf16 v[74:77], v[122:125], v[186:189], v[74:77]
	v_mfma_f32_16x16x32_bf16 v[74:77], v[134:137], v[190:193], v[74:77]
	v_mfma_f32_16x16x32_bf16 v[78:81], v[106:109], v[186:189], v[78:81]
	v_mfma_f32_16x16x32_bf16 v[78:81], v[110:113], v[190:193], v[78:81]
	v_mfma_f32_16x16x32_bf16 v[130:133], v[146:149], v[162:165], v[130:133]
	v_mfma_f32_16x16x32_bf16 v[130:133], v[150:153], v[166:169], v[130:133]
	v_mfma_f32_16x16x32_bf16 v[126:129], v[154:157], v[162:165], v[126:129]
	v_mfma_f32_16x16x32_bf16 v[126:129], v[158:161], v[166:169], v[126:129]
	v_mfma_f32_16x16x32_bf16 v[98:101], v[154:157], v[170:173], v[98:101]
	v_mfma_f32_16x16x32_bf16 v[98:101], v[158:161], v[174:177], v[98:101]
	v_mfma_f32_16x16x32_bf16 v[102:105], v[146:149], v[170:173], v[102:105]
	v_mfma_f32_16x16x32_bf16 v[102:105], v[150:153], v[174:177], v[102:105]
	v_mfma_f32_16x16x32_bf16 v[86:89], v[146:149], v[178:181], v[86:89]
	v_mfma_f32_16x16x32_bf16 v[86:89], v[150:153], v[182:185], v[86:89]
	v_mfma_f32_16x16x32_bf16 v[82:85], v[154:157], v[178:181], v[82:85]
	v_mfma_f32_16x16x32_bf16 v[82:85], v[158:161], v[182:185], v[82:85]
	v_mfma_f32_16x16x32_bf16 v[66:69], v[154:157], v[186:189], v[66:69]
	v_mfma_f32_16x16x32_bf16 v[66:69], v[158:161], v[190:193], v[66:69]
	v_mfma_f32_16x16x32_bf16 v[70:73], v[146:149], v[186:189], v[70:73]
	v_mfma_f32_16x16x32_bf16 v[70:73], v[150:153], v[190:193], v[70:73]
	s_barrier
	s_add_i32 s53, s53, s7
	v_lshl_add_u64 v[204:205], s[28:29], 0, v[0:1]
	s_mov_b32 m0, s53
	ds_read_b128 v[162:165], v249 offset:16384
	ds_read_b128 v[166:169], v249 offset:17408
	ds_read_b128 v[170:173], v249 offset:18432
	ds_read_b128 v[174:177], v249 offset:19456
	ds_read_b128 v[178:181], v249 offset:20480
	ds_read_b128 v[182:185], v249 offset:21504
	ds_read_b128 v[186:189], v249 offset:22528
	ds_read_b128 v[190:193], v249 offset:23552
	global_load_lds_dwordx4 v[204:205], off
	s_add_i32 m0, s53, 0x2000
	s_add_u32 s54, s28, 0x80000
	v_lshl_add_u64 v[206:207], s[28:29], 0, v[194:195]
	s_addc_u32 s55, s29, 0
	s_add_i32 s53, s56, s7
	global_load_lds_dwordx4 v[206:207], off
	v_lshl_add_u64 v[208:209], s[54:55], 0, v[0:1]
	s_mov_b32 m0, s53
	v_lshl_add_u64 v[210:211], s[30:31], 0, v[196:197]
	global_load_lds_dwordx4 v[208:209], off
	v_lshl_add_u64 v[208:209], s[54:55], 0, v[194:195]
	s_add_i32 m0, s53, 0x2000
	s_nop 0
	global_load_lds_dwordx4 v[208:209], off
	v_lshl_add_u64 v[208:209], s[30:31], 0, v[198:199]
	s_mov_b32 m0, s8
	s_nop 0
	global_load_lds_dwordx4 v[208:209], off
	s_mov_b32 m0, s9
	s_nop 0
	global_load_lds_dwordx4 v[210:211], off
	s_waitcnt vmcnt(8)
	s_waitcnt lgkmcnt(0)
	s_barrier
; #define PG8_STAGE(bufoff, gbase, voff) do { _Pragma("unroll") for (int _i = 0; _i < 2; ++_i) \
;         __builtin_amdgcn_global_load_lds((const unsigned*)((const char*)(gbase) + (voff)[_i]), (LAS unsigned*)(lds + (bufoff) + ldsw + _i * 8192), 16, 0, 0); } while (0)
; #define PG8_LDA(dst, b, h) do { _Pragma("unroll") for (int m = 0; m < 4; ++m) _Pragma("unroll") for (int k = 0; k < 2; ++k) dst[m][k] = *(const LAS bf16x8*)(lds + PG8_SA(b, h) + aoff + m * 2048 + k * 1024); } while (0)
; #define PG8_LDB(dst, b, h) do { _Pragma("unroll") for (int n = 0; n < 2; ++n) _Pragma("unroll") for (int k = 0; k < 2; ++k) dst[n][k] = *(const LAS bf16x8*)(lds + PG8_SB(b, h) + boff + n * 2048 + k * 1024); } while (0)
; #define PG8_MMA(ai, bj, At, Bt) do { __builtin_amdgcn_s_setprio(1); _Pragma("unroll") for (int m = 0; m < 4; ++m) _Pragma("unroll") for (int n = 0; n < 2; ++n) _Pragma("unroll") for (int k = 0; k < 2; ++k) \
;         acc[ai][bj][m][n] = __builtin_amdgcn_mfma_f32_16x16x32_bf16(Bt[n][k], At[m][k], acc[ai][bj][m][n], 0, 0, 0); __builtin_amdgcn_s_setprio(0); } while (0)
; #define PG8_WAIT_V(n) asm volatile("s_waitcnt vmcnt(" #n ")" ::: "memory")
; #define PG8_WAIT_L(n) asm volatile("s_waitcnt lgkmcnt(" #n ")" ::: "memory")
; #define PG8_BAR __builtin_amdgcn_s_barrier()
; #define PG8_SCHED __builtin_amdgcn_sched_barrier(0)
; template <class Epi, class Sched, bool ALIGN_EPI = false, bool SP2 = false>
; __device__ __forceinline__ void gemm_phase(LAS unsigned char* lds, const Gemm g, const Sched& S, const Epi& E) {
;     ...
;             PG8_WAIT_V(8); PG8_WAIT_L(0); PG8_BAR; PG8_MMA(1, 0, At, B0); PG8_MMA(1, 1, At, B1); PG8_BAR; PG8_SCHED;
;             PG8_LDB(B0, 1, 0); PG8_LDB(B1, 1, 1); PG8_SCHED; PG8_LDA(At, 1, 0); PG8_STAGE(PG8_SA(0, 1), a2 + hstep, voffA);
;             PG8_WAIT_V(8); PG8_WAIT_L(0); PG8_BAR; PG8_MMA(0, 0, At, B0); PG8_MMA(0, 1, At, B1); PG8_BAR; PG8_SCHED;
	v_mfma_f32_16x16x32_bf16 v[62:65], v[106:109], v[162:165], v[62:65]
	v_mfma_f32_16x16x32_bf16 v[62:65], v[110:113], v[166:169], v[62:65]
	v_mfma_f32_16x16x32_bf16 v[58:61], v[122:125], v[162:165], v[58:61]
	v_mfma_f32_16x16x32_bf16 v[58:61], v[134:137], v[166:169], v[58:61]
	v_mfma_f32_16x16x32_bf16 v[42:45], v[122:125], v[170:173], v[42:45]
	v_mfma_f32_16x16x32_bf16 v[42:45], v[134:137], v[174:177], v[42:45]
	v_mfma_f32_16x16x32_bf16 v[46:49], v[106:109], v[170:173], v[46:49]
	v_mfma_f32_16x16x32_bf16 v[46:49], v[110:113], v[174:177], v[46:49]
	v_mfma_f32_16x16x32_bf16 v[30:33], v[106:109], v[178:181], v[30:33]
	v_mfma_f32_16x16x32_bf16 v[30:33], v[110:113], v[182:185], v[30:33]
	v_mfma_f32_16x16x32_bf16 v[26:29], v[122:125], v[178:181], v[26:29]
	v_mfma_f32_16x16x32_bf16 v[26:29], v[134:137], v[182:185], v[26:29]
	v_mfma_f32_16x16x32_bf16 v[10:13], v[122:125], v[186:189], v[10:13]
	v_mfma_f32_16x16x32_bf16 v[10:13], v[134:137], v[190:193], v[10:13]
	v_mfma_f32_16x16x32_bf16 v[14:17], v[106:109], v[186:189], v[14:17]
	v_mfma_f32_16x16x32_bf16 v[14:17], v[110:113], v[190:193], v[14:17]
	v_mfma_f32_16x16x32_bf16 v[54:57], v[146:149], v[162:165], v[54:57]
	v_mfma_f32_16x16x32_bf16 v[54:57], v[150:153], v[166:169], v[54:57]
	v_mfma_f32_16x16x32_bf16 v[50:53], v[154:157], v[162:165], v[50:53]
	v_mfma_f32_16x16x32_bf16 v[50:53], v[158:161], v[166:169], v[50:53]
	v_mfma_f32_16x16x32_bf16 v[34:37], v[154:157], v[170:173], v[34:37]
	v_mfma_f32_16x16x32_bf16 v[34:37], v[158:161], v[174:177], v[34:37]
	v_mfma_f32_16x16x32_bf16 v[38:41], v[146:149], v[170:173], v[38:41]
	v_mfma_f32_16x16x32_bf16 v[38:41], v[150:153], v[174:177], v[38:41]
	v_mfma_f32_16x16x32_bf16 v[22:25], v[146:149], v[178:181], v[22:25]
	v_mfma_f32_16x16x32_bf16 v[22:25], v[150:153], v[182:185], v[22:25]
	v_mfma_f32_16x16x32_bf16 v[18:21], v[154:157], v[178:181], v[18:21]
	v_mfma_f32_16x16x32_bf16 v[18:21], v[158:161], v[182:185], v[18:21]
	v_mfma_f32_16x16x32_bf16 v[2:5], v[154:157], v[186:189], v[2:5]
	v_mfma_f32_16x16x32_bf16 v[2:5], v[158:161], v[190:193], v[2:5]
	v_mfma_f32_16x16x32_bf16 v[6:9], v[146:149], v[186:189], v[6:9]
	v_mfma_f32_16x16x32_bf16 v[6:9], v[150:153], v[190:193], v[6:9]
	s_barrier
	s_add_i32 s53, 0, 0x18000
	s_add_i32 s54, 0, 0x1c000
	v_add_u32_e32 v134, s53, v247
	v_add_u32_e32 v158, s54, v247
	ds_read_b128 v[106:109], v134
	ds_read_b128 v[110:113], v134 offset:1024
	ds_read_b128 v[122:125], v134 offset:2048
	ds_read_b128 v[134:137], v134 offset:3072
	ds_read_b128 v[146:149], v158
	ds_read_b128 v[150:153], v158 offset:1024
	ds_read_b128 v[154:157], v158 offset:2048
	ds_read_b128 v[158:161], v158 offset:3072
	s_add_u32 s30, s30, 0x80000
	s_addc_u32 s31, s31, 0
	s_mov_b32 m0, s35
	v_lshl_add_u64 v[212:213], s[30:31], 0, v[198:199]
	ds_read_b128 v[162:165], v249 offset:32768
	ds_read_b128 v[166:169], v249 offset:33792
	ds_read_b128 v[170:173], v249 offset:34816
	ds_read_b128 v[174:177], v249 offset:35840
	ds_read_b128 v[178:181], v249 offset:36864
	ds_read_b128 v[182:185], v249 offset:37888
	ds_read_b128 v[186:189], v249 offset:38912
	ds_read_b128 v[190:193], v249 offset:39936
	global_load_lds_dwordx4 v[212:213], off
	v_lshl_add_u64 v[212:213], s[30:31], 0, v[196:197]
	s_mov_b32 m0, s42
	s_nop 0
	global_load_lds_dwordx4 v[212:213], off
	s_waitcnt vmcnt(8)
	s_waitcnt lgkmcnt(0)
	s_barrier
	v_mfma_f32_16x16x32_bf16 v[142:145], v[106:109], v[162:165], v[142:145]
	v_mfma_f32_16x16x32_bf16 v[142:145], v[110:113], v[166:169], v[142:145]
	v_mfma_f32_16x16x32_bf16 v[138:141], v[122:125], v[162:165], v[138:141]
	v_mfma_f32_16x16x32_bf16 v[138:141], v[134:137], v[166:169], v[138:141]
	v_mfma_f32_16x16x32_bf16 v[114:117], v[122:125], v[170:173], v[114:117]
	v_mfma_f32_16x16x32_bf16 v[114:117], v[134:137], v[174:177], v[114:117]
	v_mfma_f32_16x16x32_bf16 v[118:121], v[106:109], v[170:173], v[118:121]
	v_mfma_f32_16x16x32_bf16 v[118:121], v[110:113], v[174:177], v[118:121]
	v_mfma_f32_16x16x32_bf16 v[94:97], v[106:109], v[178:181], v[94:97]
	v_mfma_f32_16x16x32_bf16 v[94:97], v[110:113], v[182:185], v[94:97]
	v_mfma_f32_16x16x32_bf16 v[90:93], v[122:125], v[178:181], v[90:93]
	v_mfma_f32_16x16x32_bf16 v[90:93], v[134:137], v[182:185], v[90:93]
	v_mfma_f32_16x16x32_bf16 v[74:77], v[122:125], v[186:189], v[74:77]
	v_mfma_f32_16x16x32_bf16 v[74:77], v[134:137], v[190:193], v[74:77]
	v_mfma_f32_16x16x32_bf16 v[78:81], v[106:109], v[186:189], v[78:81]
	v_mfma_f32_16x16x32_bf16 v[78:81], v[110:113], v[190:193], v[78:81]
	v_mfma_f32_16x16x32_bf16 v[130:133], v[146:149], v[162:165], v[130:133]
	v_mfma_f32_16x16x32_bf16 v[130:133], v[150:153], v[166:169], v[130:133]
	v_mfma_f32_16x16x32_bf16 v[126:129], v[154:157], v[162:165], v[126:129]
	v_mfma_f32_16x16x32_bf16 v[126:129], v[158:161], v[166:169], v[126:129]
	v_mfma_f32_16x16x32_bf16 v[98:101], v[154:157], v[170:173], v[98:101]
	v_mfma_f32_16x16x32_bf16 v[98:101], v[158:161], v[174:177], v[98:101]
	v_mfma_f32_16x16x32_bf16 v[102:105], v[146:149], v[170:173], v[102:105]
	v_mfma_f32_16x16x32_bf16 v[102:105], v[150:153], v[174:177], v[102:105]
	v_mfma_f32_16x16x32_bf16 v[86:89], v[146:149], v[178:181], v[86:89]
	v_mfma_f32_16x16x32_bf16 v[86:89], v[150:153], v[182:185], v[86:89]
	v_mfma_f32_16x16x32_bf16 v[82:85], v[154:157], v[178:181], v[82:85]
	v_mfma_f32_16x16x32_bf16 v[82:85], v[158:161], v[182:185], v[82:85]
	v_mfma_f32_16x16x32_bf16 v[66:69], v[154:157], v[186:189], v[66:69]
	v_mfma_f32_16x16x32_bf16 v[66:69], v[158:161], v[190:193], v[66:69]
	v_mfma_f32_16x16x32_bf16 v[70:73], v[146:149], v[186:189], v[70:73]
	v_mfma_f32_16x16x32_bf16 v[70:73], v[150:153], v[190:193], v[70:73]
	s_barrier
; #define PG8_STAGE(bufoff, gbase, voff) do { _Pragma("unroll") for (int _i = 0; _i < 2; ++_i) \
;         __builtin_amdgcn_global_load_lds((const unsigned*)((const char*)(gbase) + (voff)[_i]), (LAS unsigned*)(lds + (bufoff) + ldsw + _i * 8192), 16, 0, 0); } while (0)
; #define PG8_LDA(dst, b, h) do { _Pragma("unroll") for (int m = 0; m < 4; ++m) _Pragma("unroll") for (int k = 0; k < 2; ++k) dst[m][k] = *(const LAS bf16x8*)(lds + PG8_SA(b, h) + aoff + m * 2048 + k * 1024); } while (0)
; #define PG8_MMA(ai, bj, At, Bt) do { __builtin_amdgcn_s_setprio(1); _Pragma("unroll") for (int m = 0; m < 4; ++m) _Pragma("unroll") for (int n = 0; n < 2; ++n) _Pragma("unroll") for (int k = 0; k < 2; ++k) \
;         acc[ai][bj][m][n] = __builtin_amdgcn_mfma_f32_16x16x32_bf16(Bt[n][k], At[m][k], acc[ai][bj][m][n], 0, 0, 0); __builtin_amdgcn_s_setprio(0); } while (0)
; #define PG8_WAIT_V(n) asm volatile("s_waitcnt vmcnt(" #n ")" ::: "memory")
; #define PG8_WAIT_L(n) asm volatile("s_waitcnt lgkmcnt(" #n ")" ::: "memory")
; #define PG8_BAR __builtin_amdgcn_s_barrier()
; #define PG8_SCHED __builtin_amdgcn_sched_barrier(0)
; template <class Epi, class Sched, bool ALIGN_EPI = false, bool SP2 = false>
; __device__ __forceinline__ void gemm_phase(LAS unsigned char* lds, const Gemm g, const Sched& S, const Epi& E) {
;     ...
;             PG8_LDA(At, 1, 1); PG8_STAGE(PG8_SB(1, 0), b3, voffB); PG8_STAGE(PG8_SB(1, 1), b3 + hstep, voffB); PG8_STAGE(PG8_SA(1, 0), a3, voffA);
;             PG8_WAIT_V(8); PG8_WAIT_L(0); PG8_BAR; PG8_MMA(1, 0, At, B0); PG8_MMA(1, 1, At, B1); PG8_BAR; PG8_SCHED;
;     ...
;         if constexpr (ALIGN_EPI) { if (wr == 0) PG8_BAR; }
	s_add_i32 s30, s53, s7
	v_lshl_add_u64 v[204:205], v[204:205], 0, s[12:13]
	s_mov_b32 m0, s30
	ds_read_b128 v[162:165], v249 offset:49152
	ds_read_b128 v[166:169], v249 offset:50176
	ds_read_b128 v[170:173], v249 offset:51200
	ds_read_b128 v[174:177], v249 offset:52224
	ds_read_b128 v[178:181], v249 offset:53248
	ds_read_b128 v[182:185], v249 offset:54272
	ds_read_b128 v[186:189], v249 offset:55296
	ds_read_b128 v[190:193], v249 offset:56320
	global_load_lds_dwordx4 v[204:205], off
	s_add_i32 m0, s30, 0x2000
	s_add_u32 s28, s28, 0x80080
	v_lshl_add_u64 v[204:205], v[206:207], 0, s[12:13]
	s_addc_u32 s29, s29, 0
	s_add_i32 s30, s54, s7
	global_load_lds_dwordx4 v[204:205], off
	v_lshl_add_u64 v[204:205], s[28:29], 0, v[0:1]
	s_mov_b32 m0, s30
	s_nop 0
	global_load_lds_dwordx4 v[204:205], off
	v_lshl_add_u64 v[204:205], s[28:29], 0, v[194:195]
	s_add_i32 m0, s30, 0x2000
	s_nop 0
	global_load_lds_dwordx4 v[204:205], off
	v_lshl_add_u64 v[204:205], v[208:209], 0, s[12:13]
	s_mov_b32 m0, s43
	s_nop 0
	global_load_lds_dwordx4 v[204:205], off
	v_lshl_add_u64 v[204:205], v[210:211], 0, s[12:13]
	s_mov_b32 m0, s44
	s_nop 0
	global_load_lds_dwordx4 v[204:205], off
	s_waitcnt vmcnt(8)
	s_waitcnt lgkmcnt(0)
	s_barrier
	v_mfma_f32_16x16x32_bf16 v[62:65], v[106:109], v[162:165], v[62:65]
	v_mfma_f32_16x16x32_bf16 v[62:65], v[110:113], v[166:169], v[62:65]
	v_mfma_f32_16x16x32_bf16 v[58:61], v[122:125], v[162:165], v[58:61]
	v_mfma_f32_16x16x32_bf16 v[58:61], v[134:137], v[166:169], v[58:61]
	v_mfma_f32_16x16x32_bf16 v[42:45], v[122:125], v[170:173], v[42:45]
	v_mfma_f32_16x16x32_bf16 v[42:45], v[134:137], v[174:177], v[42:45]
	v_mfma_f32_16x16x32_bf16 v[46:49], v[106:109], v[170:173], v[46:49]
	v_mfma_f32_16x16x32_bf16 v[46:49], v[110:113], v[174:177], v[46:49]
	v_mfma_f32_16x16x32_bf16 v[30:33], v[106:109], v[178:181], v[30:33]
	v_mfma_f32_16x16x32_bf16 v[30:33], v[110:113], v[182:185], v[30:33]
	v_mfma_f32_16x16x32_bf16 v[26:29], v[122:125], v[178:181], v[26:29]
	v_mfma_f32_16x16x32_bf16 v[26:29], v[134:137], v[182:185], v[26:29]
	v_mfma_f32_16x16x32_bf16 v[10:13], v[122:125], v[186:189], v[10:13]
	v_mfma_f32_16x16x32_bf16 v[10:13], v[134:137], v[190:193], v[10:13]
	v_mfma_f32_16x16x32_bf16 v[14:17], v[106:109], v[186:189], v[14:17]
	v_mfma_f32_16x16x32_bf16 v[14:17], v[110:113], v[190:193], v[14:17]
	v_mfma_f32_16x16x32_bf16 v[54:57], v[146:149], v[162:165], v[54:57]
	v_mfma_f32_16x16x32_bf16 v[54:57], v[150:153], v[166:169], v[54:57]
	v_mfma_f32_16x16x32_bf16 v[50:53], v[154:157], v[162:165], v[50:53]
	v_mfma_f32_16x16x32_bf16 v[50:53], v[158:161], v[166:169], v[50:53]
	v_mfma_f32_16x16x32_bf16 v[34:37], v[154:157], v[170:173], v[34:37]
	v_mfma_f32_16x16x32_bf16 v[34:37], v[158:161], v[174:177], v[34:37]
	v_mfma_f32_16x16x32_bf16 v[38:41], v[146:149], v[170:173], v[38:41]
	v_mfma_f32_16x16x32_bf16 v[38:41], v[150:153], v[174:177], v[38:41]
	v_mfma_f32_16x16x32_bf16 v[22:25], v[146:149], v[178:181], v[22:25]
	v_mfma_f32_16x16x32_bf16 v[22:25], v[150:153], v[182:185], v[22:25]
	v_mfma_f32_16x16x32_bf16 v[18:21], v[154:157], v[178:181], v[18:21]
	v_mfma_f32_16x16x32_bf16 v[18:21], v[158:161], v[182:185], v[18:21]
	v_mfma_f32_16x16x32_bf16 v[2:5], v[154:157], v[186:189], v[2:5]
	v_mfma_f32_16x16x32_bf16 v[2:5], v[158:161], v[190:193], v[2:5]
	v_mfma_f32_16x16x32_bf16 v[6:9], v[146:149], v[186:189], v[6:9]
	v_mfma_f32_16x16x32_bf16 v[6:9], v[150:153], v[190:193], v[6:9]
	s_barrier
	s_add_i32 s52, s52, 2
	s_add_u32 s26, s26, 0x100
	s_addc_u32 s27, s27, 0
	s_add_u32 s50, s50, 0x100
	s_addc_u32 s51, s51, 0
	s_cmp_gt_u32 s52, 29
	s_cbranch_scc0 .LBB0_833
	s_and_b64 vcc, exec, s[16:17]
	s_cbranch_vccz .LBB0_836
	s_barrier

; #define PG8_STAGE(bufoff, gbase, voff) do { _Pragma("unroll") for (int _i = 0; _i < 2; ++_i) \
;         __builtin_amdgcn_global_load_lds((const unsigned*)((const char*)(gbase) + (voff)[_i]), (LAS unsigned*)(lds + (bufoff) + ldsw + _i * 8192), 16, 0, 0); } while (0)
; #define PG8_LDA(dst, b, h) do { _Pragma("unroll") for (int m = 0; m < 4; ++m) _Pragma("unroll") for (int k = 0; k < 2; ++k) dst[m][k] = *(const LAS bf16x8*)(lds + PG8_SA(b, h) + aoff + m * 2048 + k * 1024); } while (0)
; #define PG8_LDB(dst, b, h) do { _Pragma("unroll") for (int n = 0; n < 2; ++n) _Pragma("unroll") for (int k = 0; k < 2; ++k) dst[n][k] = *(const LAS bf16x8*)(lds + PG8_SB(b, h) + boff + n * 2048 + k * 1024); } while (0)
; #define PG8_MMA(ai, bj, At, Bt) do { __builtin_amdgcn_s_setprio(1); _Pragma("unroll") for (int m = 0; m < 4; ++m) _Pragma("unroll") for (int n = 0; n < 2; ++n) _Pragma("unroll") for (int k = 0; k < 2; ++k) \
;         acc[ai][bj][m][n] = __builtin_amdgcn_mfma_f32_16x16x32_bf16(Bt[n][k], At[m][k], acc[ai][bj][m][n], 0, 0, 0); __builtin_amdgcn_s_setprio(0); } while (0)
; template <class Epi, class Sched, bool ALIGN_EPI = false, bool SP2 = false>
; __device__ __forceinline__ void gemm_phase(LAS unsigned char* lds, const Gemm g, const Sched& S, const Epi& E) {
;     ...
;         const char* nA = has_next ? (const char*)g.A + (size_t)nxt.pm * tstep : cA; const char* nB = has_next ? (const char*)g.Bt + (size_t)nxt.pn * tstep : cB;
;         for (int t = 0; t < nt; t += 2) {
;             const bool last = (t == nt - 2);
;             const char* a1 = cA + (size_t)(t + 1) * kstep;
;             const char* a2 = last ? nA : cA + (size_t)(t + 2) * kstep; const char* b2 = last ? nB : cB + (size_t)(t + 2) * kstep;
;             const char* a3 = a2 + kstep; const char* b3 = b2 + kstep;
;             if (last && has_next) S.a_ready(nxt);
;             if constexpr (SP2) {
;             PG8_LDB(B0, 0, 0); PG8_LDB(B1, 0, 1); PG8_SCHED; PG8_LDA(At, 0, 0); PG8_STAGE(PG8_SA(1, 1), a1 + hstep, voffA);
;             PG8_WAIT_V(8); PG8_WAIT_L(0); PG8_BAR; PG8_MMA(0, 0, At, B0); PG8_MMA(0, 1, At, B1); PG8_BAR; PG8_SCHED;
;             PG8_LDA(At, 0, 1); PG8_STAGE(PG8_SB(0, 0), b2, voffB); PG8_STAGE(PG8_SB(0, 1), b2 + hstep, voffB); PG8_STAGE(PG8_SA(0, 0), a2, voffA);
;             PG8_WAIT_V(8); PG8_WAIT_L(0); PG8_BAR; PG8_MMA(1, 0, At, B0); PG8_MMA(1, 1, At, B1); PG8_BAR; PG8_SCHED;
.LBB0_924:
	s_add_u32 s28, s26, 0xfff80080
	s_addc_u32 s29, s27, -1
	s_add_i32 s51, 0, 0x10000
	s_cmp_eq_u32 s50, 28
	s_cselect_b32 s31, s7, s29
	s_cselect_b32 s30, s8, s28
	v_add_u32_e32 v148, s51, v151
	s_cselect_b32 s29, s19, s49
	s_cselect_b32 s28, s21, s35
	s_add_i32 s54, 0, 0x14000
	ds_read_b128 v[140:143], v148
	ds_read_b128 v[144:147], v148 offset:1024
	ds_read_b128 v[156:159], v148 offset:2048
	ds_read_b128 v[160:163], v148 offset:3072
	v_add_u32_e32 v148, s54, v151
	ds_read_b128 v[164:167], v148
	ds_read_b128 v[168:171], v148 offset:1024
	ds_read_b128 v[172:175], v148 offset:2048
	ds_read_b128 v[176:179], v148 offset:3072
	v_lshl_add_u64 v[212:213], s[26:27], 0, v[136:137]
	s_add_i32 m0, s42, 0xc000
	ds_read_b128 v[180:183], v155
	ds_read_b128 v[184:187], v155 offset:1024
	ds_read_b128 v[188:191], v155 offset:2048
	ds_read_b128 v[192:195], v155 offset:3072
	ds_read_b128 v[196:199], v155 offset:4096
	ds_read_b128 v[200:203], v155 offset:5120
	ds_read_b128 v[204:207], v155 offset:6144
	ds_read_b128 v[208:211], v155 offset:7168
	global_load_lds_dwordx4 v[212:213], off
	v_lshl_add_u64 v[212:213], s[26:27], 0, v[138:139]
	s_add_i32 m0, s42, 0xe000
	s_nop 0
	global_load_lds_dwordx4 v[212:213], off
	s_waitcnt vmcnt(8)
	s_waitcnt lgkmcnt(0)
	s_barrier
	v_mfma_f32_16x16x32_bf16 v[126:129], v[140:143], v[180:183], v[126:129]
	v_mfma_f32_16x16x32_bf16 v[126:129], v[144:147], v[184:187], v[126:129]
	v_mfma_f32_16x16x32_bf16 v[122:125], v[156:159], v[180:183], v[122:125]
	v_mfma_f32_16x16x32_bf16 v[122:125], v[160:163], v[184:187], v[122:125]
	v_mfma_f32_16x16x32_bf16 v[106:109], v[156:159], v[188:191], v[106:109]
	v_mfma_f32_16x16x32_bf16 v[106:109], v[160:163], v[192:195], v[106:109]
	v_mfma_f32_16x16x32_bf16 v[110:113], v[140:143], v[188:191], v[110:113]
	v_mfma_f32_16x16x32_bf16 v[110:113], v[144:147], v[192:195], v[110:113]
	v_mfma_f32_16x16x32_bf16 v[94:97], v[140:143], v[196:199], v[94:97]
	v_mfma_f32_16x16x32_bf16 v[94:97], v[144:147], v[200:203], v[94:97]
	v_mfma_f32_16x16x32_bf16 v[90:93], v[156:159], v[196:199], v[90:93]
	v_mfma_f32_16x16x32_bf16 v[90:93], v[160:163], v[200:203], v[90:93]
	v_mfma_f32_16x16x32_bf16 v[74:77], v[156:159], v[204:207], v[74:77]
	v_mfma_f32_16x16x32_bf16 v[74:77], v[160:163], v[208:211], v[74:77]
	v_mfma_f32_16x16x32_bf16 v[78:81], v[140:143], v[204:207], v[78:81]
	v_mfma_f32_16x16x32_bf16 v[78:81], v[144:147], v[208:211], v[78:81]
	v_mfma_f32_16x16x32_bf16 v[118:121], v[164:167], v[180:183], v[118:121]
	v_mfma_f32_16x16x32_bf16 v[118:121], v[168:171], v[184:187], v[118:121]
	v_mfma_f32_16x16x32_bf16 v[114:117], v[172:175], v[180:183], v[114:117]
	v_mfma_f32_16x16x32_bf16 v[114:117], v[176:179], v[184:187], v[114:117]
	v_mfma_f32_16x16x32_bf16 v[98:101], v[172:175], v[188:191], v[98:101]
	v_mfma_f32_16x16x32_bf16 v[98:101], v[176:179], v[192:195], v[98:101]
	v_mfma_f32_16x16x32_bf16 v[102:105], v[164:167], v[188:191], v[102:105]
	v_mfma_f32_16x16x32_bf16 v[102:105], v[168:171], v[192:195], v[102:105]
	v_mfma_f32_16x16x32_bf16 v[86:89], v[164:167], v[196:199], v[86:89]
	v_mfma_f32_16x16x32_bf16 v[86:89], v[168:171], v[200:203], v[86:89]
	v_mfma_f32_16x16x32_bf16 v[82:85], v[172:175], v[196:199], v[82:85]
	v_mfma_f32_16x16x32_bf16 v[82:85], v[176:179], v[200:203], v[82:85]
	v_mfma_f32_16x16x32_bf16 v[66:69], v[172:175], v[204:207], v[66:69]
	v_mfma_f32_16x16x32_bf16 v[66:69], v[176:179], v[208:211], v[66:69]
	v_mfma_f32_16x16x32_bf16 v[70:73], v[164:167], v[204:207], v[70:73]
	v_mfma_f32_16x16x32_bf16 v[70:73], v[168:171], v[208:211], v[70:73]
	s_barrier
	s_add_i32 s51, s51, s41
	v_lshl_add_u64 v[212:213], s[28:29], 0, v[0:1]
	s_mov_b32 m0, s51
	ds_read_b128 v[180:183], v155 offset:16384
	ds_read_b128 v[184:187], v155 offset:17408
	ds_read_b128 v[188:191], v155 offset:18432
	ds_read_b128 v[192:195], v155 offset:19456
	ds_read_b128 v[196:199], v155 offset:20480
	ds_read_b128 v[200:203], v155 offset:21504
	ds_read_b128 v[204:207], v155 offset:22528
	ds_read_b128 v[208:211], v155 offset:23552
	global_load_lds_dwordx4 v[212:213], off
	s_add_i32 m0, s51, 0x2000
	s_add_u32 s52, s28, 0x80000
	v_lshl_add_u64 v[214:215], s[28:29], 0, v[130:131]
	s_addc_u32 s53, s29, 0
	s_add_i32 s51, s54, s41
	global_load_lds_dwordx4 v[214:215], off
	v_lshl_add_u64 v[216:217], s[52:53], 0, v[0:1]
	s_mov_b32 m0, s51
	v_lshl_add_u64 v[218:219], s[30:31], 0, v[132:133]
	global_load_lds_dwordx4 v[216:217], off
	v_lshl_add_u64 v[216:217], s[52:53], 0, v[130:131]
	s_add_i32 m0, s51, 0x2000
	s_nop 0
	global_load_lds_dwordx4 v[216:217], off
	v_lshl_add_u64 v[216:217], s[30:31], 0, v[134:135]
	s_mov_b32 m0, s42
	s_nop 0
	global_load_lds_dwordx4 v[216:217], off
	s_mov_b32 m0, s43
	s_nop 0
	global_load_lds_dwordx4 v[218:219], off
	s_waitcnt vmcnt(8)
	s_waitcnt lgkmcnt(0)
	s_barrier
; #define PG8_STAGE(bufoff, gbase, voff) do { _Pragma("unroll") for (int _i = 0; _i < 2; ++_i) \
;         __builtin_amdgcn_global_load_lds((const unsigned*)((const char*)(gbase) + (voff)[_i]), (LAS unsigned*)(lds + (bufoff) + ldsw + _i * 8192), 16, 0, 0); } while (0)
; #define PG8_LDA(dst, b, h) do { _Pragma("unroll") for (int m = 0; m < 4; ++m) _Pragma("unroll") for (int k = 0; k < 2; ++k) dst[m][k] = *(const LAS bf16x8*)(lds + PG8_SA(b, h) + aoff + m * 2048 + k * 1024); } while (0)
; #define PG8_LDB(dst, b, h) do { _Pragma("unroll") for (int n = 0; n < 2; ++n) _Pragma("unroll") for (int k = 0; k < 2; ++k) dst[n][k] = *(const LAS bf16x8*)(lds + PG8_SB(b, h) + boff + n * 2048 + k * 1024); } while (0)
; #define PG8_MMA(ai, bj, At, Bt) do { __builtin_amdgcn_s_setprio(1); _Pragma("unroll") for (int m = 0; m < 4; ++m) _Pragma("unroll") for (int n = 0; n < 2; ++n) _Pragma("unroll") for (int k = 0; k < 2; ++k) \
;         acc[ai][bj][m][n] = __builtin_amdgcn_mfma_f32_16x16x32_bf16(Bt[n][k], At[m][k], acc[ai][bj][m][n], 0, 0, 0); __builtin_amdgcn_s_setprio(0); } while (0)
; #define PG8_WAIT_V(n) asm volatile("s_waitcnt vmcnt(" #n ")" ::: "memory")
; #define PG8_WAIT_L(n) asm volatile("s_waitcnt lgkmcnt(" #n ")" ::: "memory")
; #define PG8_BAR __builtin_amdgcn_s_barrier()
; #define PG8_SCHED __builtin_amdgcn_sched_barrier(0)
; template <class Epi, class Sched, bool ALIGN_EPI = false, bool SP2 = false>
; __device__ __forceinline__ void gemm_phase(LAS unsigned char* lds, const Gemm g, const Sched& S, const Epi& E) {
;     ...
;             PG8_WAIT_V(8); PG8_WAIT_L(0); PG8_BAR; PG8_MMA(1, 0, At, B0); PG8_MMA(1, 1, At, B1); PG8_BAR; PG8_SCHED;
;             PG8_LDB(B0, 1, 0); PG8_LDB(B1, 1, 1); PG8_SCHED; PG8_LDA(At, 1, 0); PG8_STAGE(PG8_SA(0, 1), a2 + hstep, voffA);
;             PG8_WAIT_V(8); PG8_WAIT_L(0); PG8_BAR; PG8_MMA(0, 0, At, B0); PG8_MMA(0, 1, At, B1); PG8_BAR; PG8_SCHED;
	v_mfma_f32_16x16x32_bf16 v[62:65], v[140:143], v[180:183], v[62:65]
	v_mfma_f32_16x16x32_bf16 v[62:65], v[144:147], v[184:187], v[62:65]
	v_mfma_f32_16x16x32_bf16 v[58:61], v[156:159], v[180:183], v[58:61]
	v_mfma_f32_16x16x32_bf16 v[58:61], v[160:163], v[184:187], v[58:61]
	v_mfma_f32_16x16x32_bf16 v[42:45], v[156:159], v[188:191], v[42:45]
	v_mfma_f32_16x16x32_bf16 v[42:45], v[160:163], v[192:195], v[42:45]
	v_mfma_f32_16x16x32_bf16 v[46:49], v[140:143], v[188:191], v[46:49]
	v_mfma_f32_16x16x32_bf16 v[46:49], v[144:147], v[192:195], v[46:49]
	v_mfma_f32_16x16x32_bf16 v[30:33], v[140:143], v[196:199], v[30:33]
	v_mfma_f32_16x16x32_bf16 v[30:33], v[144:147], v[200:203], v[30:33]
	v_mfma_f32_16x16x32_bf16 v[26:29], v[156:159], v[196:199], v[26:29]
	v_mfma_f32_16x16x32_bf16 v[26:29], v[160:163], v[200:203], v[26:29]
	v_mfma_f32_16x16x32_bf16 v[10:13], v[156:159], v[204:207], v[10:13]
	v_mfma_f32_16x16x32_bf16 v[10:13], v[160:163], v[208:211], v[10:13]
	v_mfma_f32_16x16x32_bf16 v[14:17], v[140:143], v[204:207], v[14:17]
	v_mfma_f32_16x16x32_bf16 v[14:17], v[144:147], v[208:211], v[14:17]
	v_mfma_f32_16x16x32_bf16 v[54:57], v[164:167], v[180:183], v[54:57]
	v_mfma_f32_16x16x32_bf16 v[54:57], v[168:171], v[184:187], v[54:57]
	v_mfma_f32_16x16x32_bf16 v[50:53], v[172:175], v[180:183], v[50:53]
	v_mfma_f32_16x16x32_bf16 v[50:53], v[176:179], v[184:187], v[50:53]
	v_mfma_f32_16x16x32_bf16 v[34:37], v[172:175], v[188:191], v[34:37]
	v_mfma_f32_16x16x32_bf16 v[34:37], v[176:179], v[192:195], v[34:37]
	v_mfma_f32_16x16x32_bf16 v[38:41], v[164:167], v[188:191], v[38:41]
	v_mfma_f32_16x16x32_bf16 v[38:41], v[168:171], v[192:195], v[38:41]
	v_mfma_f32_16x16x32_bf16 v[22:25], v[164:167], v[196:199], v[22:25]
	v_mfma_f32_16x16x32_bf16 v[22:25], v[168:171], v[200:203], v[22:25]
	v_mfma_f32_16x16x32_bf16 v[18:21], v[172:175], v[196:199], v[18:21]
	v_mfma_f32_16x16x32_bf16 v[18:21], v[176:179], v[200:203], v[18:21]
	v_mfma_f32_16x16x32_bf16 v[2:5], v[172:175], v[204:207], v[2:5]
	v_mfma_f32_16x16x32_bf16 v[2:5], v[176:179], v[208:211], v[2:5]
	v_mfma_f32_16x16x32_bf16 v[6:9], v[164:167], v[204:207], v[6:9]
	v_mfma_f32_16x16x32_bf16 v[6:9], v[168:171], v[208:211], v[6:9]
	s_barrier
	s_add_i32 s51, 0, 0x18000
	v_add_u32_e32 v148, s51, v151
	s_add_i32 s52, 0, 0x1c000
	ds_read_b128 v[140:143], v148
	ds_read_b128 v[144:147], v148 offset:1024
	ds_read_b128 v[156:159], v148 offset:2048
	ds_read_b128 v[160:163], v148 offset:3072
	v_add_u32_e32 v148, s52, v151
	ds_read_b128 v[164:167], v148
	ds_read_b128 v[168:171], v148 offset:1024
	ds_read_b128 v[172:175], v148 offset:2048
	ds_read_b128 v[176:179], v148 offset:3072
	s_add_u32 s30, s30, 0x80000
	s_addc_u32 s31, s31, 0
	s_mov_b32 m0, s44
	v_lshl_add_u64 v[220:221], s[30:31], 0, v[134:135]
	ds_read_b128 v[180:183], v155 offset:32768
	ds_read_b128 v[184:187], v155 offset:33792
	ds_read_b128 v[188:191], v155 offset:34816
	ds_read_b128 v[192:195], v155 offset:35840
	ds_read_b128 v[196:199], v155 offset:36864
	ds_read_b128 v[200:203], v155 offset:37888
	ds_read_b128 v[204:207], v155 offset:38912
	ds_read_b128 v[208:211], v155 offset:39936
	global_load_lds_dwordx4 v[220:221], off
	v_lshl_add_u64 v[220:221], s[30:31], 0, v[132:133]
	s_mov_b32 m0, s45
	s_nop 0
	global_load_lds_dwordx4 v[220:221], off
	s_waitcnt vmcnt(8)
	s_waitcnt lgkmcnt(0)
	s_barrier
	v_mfma_f32_16x16x32_bf16 v[126:129], v[140:143], v[180:183], v[126:129]
	v_mfma_f32_16x16x32_bf16 v[126:129], v[144:147], v[184:187], v[126:129]
	v_mfma_f32_16x16x32_bf16 v[122:125], v[156:159], v[180:183], v[122:125]
	v_mfma_f32_16x16x32_bf16 v[122:125], v[160:163], v[184:187], v[122:125]
	v_mfma_f32_16x16x32_bf16 v[106:109], v[156:159], v[188:191], v[106:109]
	v_mfma_f32_16x16x32_bf16 v[106:109], v[160:163], v[192:195], v[106:109]
	v_mfma_f32_16x16x32_bf16 v[110:113], v[140:143], v[188:191], v[110:113]
	v_mfma_f32_16x16x32_bf16 v[110:113], v[144:147], v[192:195], v[110:113]
	v_mfma_f32_16x16x32_bf16 v[94:97], v[140:143], v[196:199], v[94:97]
	v_mfma_f32_16x16x32_bf16 v[94:97], v[144:147], v[200:203], v[94:97]
	v_mfma_f32_16x16x32_bf16 v[90:93], v[156:159], v[196:199], v[90:93]
	v_mfma_f32_16x16x32_bf16 v[90:93], v[160:163], v[200:203], v[90:93]
	v_mfma_f32_16x16x32_bf16 v[74:77], v[156:159], v[204:207], v[74:77]
	v_mfma_f32_16x16x32_bf16 v[74:77], v[160:163], v[208:211], v[74:77]
	v_mfma_f32_16x16x32_bf16 v[78:81], v[140:143], v[204:207], v[78:81]
	v_mfma_f32_16x16x32_bf16 v[78:81], v[144:147], v[208:211], v[78:81]
	v_mfma_f32_16x16x32_bf16 v[118:121], v[164:167], v[180:183], v[118:121]
	v_mfma_f32_16x16x32_bf16 v[118:121], v[168:171], v[184:187], v[118:121]
	v_mfma_f32_16x16x32_bf16 v[114:117], v[172:175], v[180:183], v[114:117]
	v_mfma_f32_16x16x32_bf16 v[114:117], v[176:179], v[184:187], v[114:117]
	v_mfma_f32_16x16x32_bf16 v[98:101], v[172:175], v[188:191], v[98:101]
	v_mfma_f32_16x16x32_bf16 v[98:101], v[176:179], v[192:195], v[98:101]
	v_mfma_f32_16x16x32_bf16 v[102:105], v[164:167], v[188:191], v[102:105]
	v_mfma_f32_16x16x32_bf16 v[102:105], v[168:171], v[192:195], v[102:105]
	v_mfma_f32_16x16x32_bf16 v[86:89], v[164:167], v[196:199], v[86:89]
	v_mfma_f32_16x16x32_bf16 v[86:89], v[168:171], v[200:203], v[86:89]
	v_mfma_f32_16x16x32_bf16 v[82:85], v[172:175], v[196:199], v[82:85]
	v_mfma_f32_16x16x32_bf16 v[82:85], v[176:179], v[200:203], v[82:85]
	v_mfma_f32_16x16x32_bf16 v[66:69], v[172:175], v[204:207], v[66:69]
	v_mfma_f32_16x16x32_bf16 v[66:69], v[176:179], v[208:211], v[66:69]
	v_mfma_f32_16x16x32_bf16 v[70:73], v[164:167], v[204:207], v[70:73]
	v_mfma_f32_16x16x32_bf16 v[70:73], v[168:171], v[208:211], v[70:73]
	s_barrier
; #define PG8_STAGE(bufoff, gbase, voff) do { _Pragma("unroll") for (int _i = 0; _i < 2; ++_i) \
;         __builtin_amdgcn_global_load_lds((const unsigned*)((const char*)(gbase) + (voff)[_i]), (LAS unsigned*)(lds + (bufoff) + ldsw + _i * 8192), 16, 0, 0); } while (0)
; #define PG8_LDA(dst, b, h) do { _Pragma("unroll") for (int m = 0; m < 4; ++m) _Pragma("unroll") for (int k = 0; k < 2; ++k) dst[m][k] = *(const LAS bf16x8*)(lds + PG8_SA(b, h) + aoff + m * 2048 + k * 1024); } while (0)
; #define PG8_MMA(ai, bj, At, Bt) do { __builtin_amdgcn_s_setprio(1); _Pragma("unroll") for (int m = 0; m < 4; ++m) _Pragma("unroll") for (int n = 0; n < 2; ++n) _Pragma("unroll") for (int k = 0; k < 2; ++k) \
;         acc[ai][bj][m][n] = __builtin_amdgcn_mfma_f32_16x16x32_bf16(Bt[n][k], At[m][k], acc[ai][bj][m][n], 0, 0, 0); __builtin_amdgcn_s_setprio(0); } while (0)
; #define PG8_WAIT_V(n) asm volatile("s_waitcnt vmcnt(" #n ")" ::: "memory")
; #define PG8_WAIT_L(n) asm volatile("s_waitcnt lgkmcnt(" #n ")" ::: "memory")
; #define PG8_BAR __builtin_amdgcn_s_barrier()
; #define PG8_SCHED __builtin_amdgcn_sched_barrier(0)
; template <class Epi, class Sched, bool ALIGN_EPI = false, bool SP2 = false>
; __device__ __forceinline__ void gemm_phase(LAS unsigned char* lds, const Gemm g, const Sched& S, const Epi& E) {
;     ...
;             PG8_LDA(At, 1, 1); PG8_STAGE(PG8_SB(1, 0), b3, voffB); PG8_STAGE(PG8_SB(1, 1), b3 + hstep, voffB); PG8_STAGE(PG8_SA(1, 0), a3, voffA);
;             PG8_WAIT_V(8); PG8_WAIT_L(0); PG8_BAR; PG8_MMA(1, 0, At, B0); PG8_MMA(1, 1, At, B1); PG8_BAR; PG8_SCHED;
;     ...
;         if constexpr (ALIGN_EPI) { if (wr == 0) PG8_BAR; }
	s_add_i32 s30, s51, s41
	v_lshl_add_u64 v[212:213], v[212:213], 0, s[12:13]
	s_mov_b32 m0, s30
	ds_read_b128 v[180:183], v155 offset:49152
	ds_read_b128 v[184:187], v155 offset:50176
	ds_read_b128 v[188:191], v155 offset:51200
	ds_read_b128 v[192:195], v155 offset:52224
	ds_read_b128 v[196:199], v155 offset:53248
	ds_read_b128 v[200:203], v155 offset:54272
	ds_read_b128 v[204:207], v155 offset:55296
	ds_read_b128 v[208:211], v155 offset:56320
	global_load_lds_dwordx4 v[212:213], off
	s_add_i32 m0, s30, 0x2000
	s_add_u32 s28, s28, 0x80080
	v_lshl_add_u64 v[212:213], v[214:215], 0, s[12:13]
	s_addc_u32 s29, s29, 0
	s_add_i32 s30, s52, s41
	global_load_lds_dwordx4 v[212:213], off
	v_lshl_add_u64 v[212:213], s[28:29], 0, v[0:1]
	s_mov_b32 m0, s30
	s_nop 0
	global_load_lds_dwordx4 v[212:213], off
	v_lshl_add_u64 v[212:213], s[28:29], 0, v[130:131]
	s_add_i32 m0, s30, 0x2000
	s_nop 0
	global_load_lds_dwordx4 v[212:213], off
	v_lshl_add_u64 v[212:213], v[216:217], 0, s[12:13]
	s_mov_b32 m0, s46
	s_nop 0
	global_load_lds_dwordx4 v[212:213], off
	v_lshl_add_u64 v[212:213], v[218:219], 0, s[12:13]
	s_mov_b32 m0, s47
	s_nop 0
	global_load_lds_dwordx4 v[212:213], off
	s_waitcnt vmcnt(8)
	s_waitcnt lgkmcnt(0)
	s_barrier
	v_mfma_f32_16x16x32_bf16 v[62:65], v[140:143], v[180:183], v[62:65]
	v_mfma_f32_16x16x32_bf16 v[62:65], v[144:147], v[184:187], v[62:65]
	v_mfma_f32_16x16x32_bf16 v[58:61], v[156:159], v[180:183], v[58:61]
	v_mfma_f32_16x16x32_bf16 v[58:61], v[160:163], v[184:187], v[58:61]
	v_mfma_f32_16x16x32_bf16 v[42:45], v[156:159], v[188:191], v[42:45]
	v_mfma_f32_16x16x32_bf16 v[42:45], v[160:163], v[192:195], v[42:45]
	v_mfma_f32_16x16x32_bf16 v[46:49], v[140:143], v[188:191], v[46:49]
	v_mfma_f32_16x16x32_bf16 v[46:49], v[144:147], v[192:195], v[46:49]
	v_mfma_f32_16x16x32_bf16 v[30:33], v[140:143], v[196:199], v[30:33]
	v_mfma_f32_16x16x32_bf16 v[30:33], v[144:147], v[200:203], v[30:33]
	v_mfma_f32_16x16x32_bf16 v[26:29], v[156:159], v[196:199], v[26:29]
	v_mfma_f32_16x16x32_bf16 v[26:29], v[160:163], v[200:203], v[26:29]
	v_mfma_f32_16x16x32_bf16 v[10:13], v[156:159], v[204:207], v[10:13]
	v_mfma_f32_16x16x32_bf16 v[10:13], v[160:163], v[208:211], v[10:13]
	v_mfma_f32_16x16x32_bf16 v[14:17], v[140:143], v[204:207], v[14:17]
	v_mfma_f32_16x16x32_bf16 v[14:17], v[144:147], v[208:211], v[14:17]
	v_mfma_f32_16x16x32_bf16 v[54:57], v[164:167], v[180:183], v[54:57]
	v_mfma_f32_16x16x32_bf16 v[54:57], v[168:171], v[184:187], v[54:57]
	v_mfma_f32_16x16x32_bf16 v[50:53], v[172:175], v[180:183], v[50:53]
	v_mfma_f32_16x16x32_bf16 v[50:53], v[176:179], v[184:187], v[50:53]
	v_mfma_f32_16x16x32_bf16 v[34:37], v[172:175], v[188:191], v[34:37]
	v_mfma_f32_16x16x32_bf16 v[34:37], v[176:179], v[192:195], v[34:37]
	v_mfma_f32_16x16x32_bf16 v[38:41], v[164:167], v[188:191], v[38:41]
	v_mfma_f32_16x16x32_bf16 v[38:41], v[168:171], v[192:195], v[38:41]
	v_mfma_f32_16x16x32_bf16 v[22:25], v[164:167], v[196:199], v[22:25]
	v_mfma_f32_16x16x32_bf16 v[22:25], v[168:171], v[200:203], v[22:25]
	v_mfma_f32_16x16x32_bf16 v[18:21], v[172:175], v[196:199], v[18:21]
	v_mfma_f32_16x16x32_bf16 v[18:21], v[176:179], v[200:203], v[18:21]
	v_mfma_f32_16x16x32_bf16 v[2:5], v[172:175], v[204:207], v[2:5]
	v_mfma_f32_16x16x32_bf16 v[2:5], v[176:179], v[208:211], v[2:5]
	v_mfma_f32_16x16x32_bf16 v[6:9], v[164:167], v[204:207], v[6:9]
	v_mfma_f32_16x16x32_bf16 v[6:9], v[168:171], v[208:211], v[6:9]
	s_barrier
	s_add_i32 s50, s50, 2
	s_add_u32 s26, s26, 0x100
	s_addc_u32 s27, s27, 0
	s_add_u32 s35, s35, 0x100
	s_addc_u32 s49, s49, 0
	s_cmp_gt_u32 s50, 29
	s_cbranch_scc0 .LBB0_924
	s_and_b64 vcc, exec, s[16:17]
	s_cbranch_vccz .LBB0_927
	s_barrier

; #define PG8_STAGE(bufoff, gbase, voff) do { _Pragma("unroll") for (int _i = 0; _i < 2; ++_i) \
;         __builtin_amdgcn_global_load_lds((const unsigned*)((const char*)(gbase) + (voff)[_i]), (LAS unsigned*)(lds + (bufoff) + ldsw + _i * 8192), 16, 0, 0); } while (0)
; #define PG8_LDA(dst, b, h) do { _Pragma("unroll") for (int m = 0; m < 4; ++m) _Pragma("unroll") for (int k = 0; k < 2; ++k) dst[m][k] = *(const LAS bf16x8*)(lds + PG8_SA(b, h) + aoff + m * 2048 + k * 1024); } while (0)
; #define PG8_LDB(dst, b, h) do { _Pragma("unroll") for (int n = 0; n < 2; ++n) _Pragma("unroll") for (int k = 0; k < 2; ++k) dst[n][k] = *(const LAS bf16x8*)(lds + PG8_SB(b, h) + boff + n * 2048 + k * 1024); } while (0)
; #define PG8_MMA(ai, bj, At, Bt) do { __builtin_amdgcn_s_setprio(1); _Pragma("unroll") for (int m = 0; m < 4; ++m) _Pragma("unroll") for (int n = 0; n < 2; ++n) _Pragma("unroll") for (int k = 0; k < 2; ++k) \
;         acc[ai][bj][m][n] = __builtin_amdgcn_mfma_f32_16x16x32_bf16(Bt[n][k], At[m][k], acc[ai][bj][m][n], 0, 0, 0); __builtin_amdgcn_s_setprio(0); } while (0)
; template <class Epi, class Sched, bool ALIGN_EPI = false, bool SP2 = false>
; __device__ __forceinline__ void gemm_phase(LAS unsigned char* lds, const Gemm g, const Sched& S, const Epi& E) {
;     ...
;         const char* nA = has_next ? (const char*)g.A + (size_t)nxt.pm * tstep : cA; const char* nB = has_next ? (const char*)g.Bt + (size_t)nxt.pn * tstep : cB;
;         for (int t = 0; t < nt; t += 2) {
;             const bool last = (t == nt - 2);
;             const char* a1 = cA + (size_t)(t + 1) * kstep;
;             const char* a2 = last ? nA : cA + (size_t)(t + 2) * kstep; const char* b2 = last ? nB : cB + (size_t)(t + 2) * kstep;
;             const char* a3 = a2 + kstep; const char* b3 = b2 + kstep;
;             if (last && has_next) S.a_ready(nxt);
;             if constexpr (SP2) {
;             PG8_LDB(B0, 0, 0); PG8_LDB(B1, 0, 1); PG8_SCHED; PG8_LDA(At, 0, 0); PG8_STAGE(PG8_SA(1, 1), a1 + hstep, voffA);
;             PG8_WAIT_V(8); PG8_WAIT_L(0); PG8_BAR; PG8_MMA(0, 0, At, B0); PG8_MMA(0, 1, At, B1); PG8_BAR; PG8_SCHED;
;             PG8_LDA(At, 0, 1); PG8_STAGE(PG8_SB(0, 0), b2, voffB); PG8_STAGE(PG8_SB(0, 1), b2 + hstep, voffB); PG8_STAGE(PG8_SA(0, 0), a2, voffA);
;             PG8_WAIT_V(8); PG8_WAIT_L(0); PG8_BAR; PG8_MMA(1, 0, At, B0); PG8_MMA(1, 1, At, B1); PG8_BAR; PG8_SCHED;
.LBB0_1007:
	s_add_u32 s24, s22, 0x100
	s_addc_u32 s25, s23, 0
	s_add_i32 s49, 0, 0x10000
	s_cmpk_eq_i32 s48, 0x54
	s_cselect_b32 s29, s1, s25
	s_cselect_b32 s28, s0, s24
	s_cselect_b32 s27, s21, s47
	s_cselect_b32 s26, s20, s46
	s_add_i32 s50, 0, 0x14000
	v_add_u32_e32 v126, s49, v247
	v_add_u32_e32 v158, s50, v247
	ds_read_b128 v[90:93], v126
	ds_read_b128 v[102:105], v126 offset:1024
	ds_read_b128 v[114:117], v126 offset:2048
	ds_read_b128 v[126:129], v126 offset:3072
	ds_read_b128 v[138:141], v158
	ds_read_b128 v[142:145], v158 offset:1024
	ds_read_b128 v[154:157], v158 offset:2048
	ds_read_b128 v[158:161], v158 offset:3072
	v_lshl_add_u64 v[204:205], s[22:23], 0, v[200:201]
	s_add_i32 m0, s8, 0xc000
	ds_read_b128 v[162:165], v249
	ds_read_b128 v[166:169], v249 offset:1024
	ds_read_b128 v[170:173], v249 offset:2048
	ds_read_b128 v[174:177], v249 offset:3072
	ds_read_b128 v[178:181], v249 offset:4096
	ds_read_b128 v[182:185], v249 offset:5120
	ds_read_b128 v[186:189], v249 offset:6144
	ds_read_b128 v[190:193], v249 offset:7168
	global_load_lds_dwordx4 v[204:205], off
	v_lshl_add_u64 v[204:205], s[22:23], 0, v[202:203]
	s_add_i32 m0, s8, 0xe000
	s_nop 0
	global_load_lds_dwordx4 v[204:205], off
	s_waitcnt vmcnt(8)
	s_waitcnt lgkmcnt(0)
	s_barrier
	v_mfma_f32_16x16x32_bf16 v[150:153], v[90:93], v[162:165], v[150:153]
	v_mfma_f32_16x16x32_bf16 v[150:153], v[102:105], v[166:169], v[150:153]
	v_mfma_f32_16x16x32_bf16 v[146:149], v[114:117], v[162:165], v[146:149]
	v_mfma_f32_16x16x32_bf16 v[146:149], v[126:129], v[166:169], v[146:149]
	v_mfma_f32_16x16x32_bf16 v[118:121], v[114:117], v[170:173], v[118:121]
	v_mfma_f32_16x16x32_bf16 v[118:121], v[126:129], v[174:177], v[118:121]
	v_mfma_f32_16x16x32_bf16 v[122:125], v[90:93], v[170:173], v[122:125]
	v_mfma_f32_16x16x32_bf16 v[122:125], v[102:105], v[174:177], v[122:125]
	v_mfma_f32_16x16x32_bf16 v[98:101], v[90:93], v[178:181], v[98:101]
	v_mfma_f32_16x16x32_bf16 v[98:101], v[102:105], v[182:185], v[98:101]
	v_mfma_f32_16x16x32_bf16 v[94:97], v[114:117], v[178:181], v[94:97]
	v_mfma_f32_16x16x32_bf16 v[94:97], v[126:129], v[182:185], v[94:97]
	v_mfma_f32_16x16x32_bf16 v[74:77], v[114:117], v[186:189], v[74:77]
	v_mfma_f32_16x16x32_bf16 v[74:77], v[126:129], v[190:193], v[74:77]
	v_mfma_f32_16x16x32_bf16 v[78:81], v[90:93], v[186:189], v[78:81]
	v_mfma_f32_16x16x32_bf16 v[78:81], v[102:105], v[190:193], v[78:81]
	v_mfma_f32_16x16x32_bf16 v[134:137], v[138:141], v[162:165], v[134:137]
	v_mfma_f32_16x16x32_bf16 v[134:137], v[142:145], v[166:169], v[134:137]
	v_mfma_f32_16x16x32_bf16 v[130:133], v[154:157], v[162:165], v[130:133]
	v_mfma_f32_16x16x32_bf16 v[130:133], v[158:161], v[166:169], v[130:133]
	v_mfma_f32_16x16x32_bf16 v[106:109], v[154:157], v[170:173], v[106:109]
	v_mfma_f32_16x16x32_bf16 v[106:109], v[158:161], v[174:177], v[106:109]
	v_mfma_f32_16x16x32_bf16 v[110:113], v[138:141], v[170:173], v[110:113]
	v_mfma_f32_16x16x32_bf16 v[110:113], v[142:145], v[174:177], v[110:113]
	v_mfma_f32_16x16x32_bf16 v[86:89], v[138:141], v[178:181], v[86:89]
	v_mfma_f32_16x16x32_bf16 v[86:89], v[142:145], v[182:185], v[86:89]
	v_mfma_f32_16x16x32_bf16 v[82:85], v[154:157], v[178:181], v[82:85]
	v_mfma_f32_16x16x32_bf16 v[82:85], v[158:161], v[182:185], v[82:85]
	v_mfma_f32_16x16x32_bf16 v[66:69], v[154:157], v[186:189], v[66:69]
	v_mfma_f32_16x16x32_bf16 v[66:69], v[158:161], v[190:193], v[66:69]
	v_mfma_f32_16x16x32_bf16 v[70:73], v[138:141], v[186:189], v[70:73]
	v_mfma_f32_16x16x32_bf16 v[70:73], v[142:145], v[190:193], v[70:73]
	s_barrier
	s_add_i32 s22, s49, s7
	v_lshl_add_u64 v[204:205], s[26:27], 0, v[0:1]
	s_mov_b32 m0, s22
	ds_read_b128 v[162:165], v249 offset:16384
	ds_read_b128 v[166:169], v249 offset:17408
	ds_read_b128 v[170:173], v249 offset:18432
	ds_read_b128 v[174:177], v249 offset:19456
	ds_read_b128 v[178:181], v249 offset:20480
	ds_read_b128 v[182:185], v249 offset:21504
	ds_read_b128 v[186:189], v249 offset:22528
	ds_read_b128 v[190:193], v249 offset:23552
	global_load_lds_dwordx4 v[204:205], off
	s_add_i32 m0, s22, 0x2000
	s_add_u32 s22, s26, 0x160000
	v_lshl_add_u64 v[206:207], s[26:27], 0, v[194:195]
	s_addc_u32 s23, s27, 0
	s_add_i32 s49, s50, s7
	global_load_lds_dwordx4 v[206:207], off
	v_lshl_add_u64 v[208:209], s[22:23], 0, v[0:1]
	s_mov_b32 m0, s49
	v_lshl_add_u64 v[210:211], s[28:29], 0, v[196:197]
	global_load_lds_dwordx4 v[208:209], off
	v_lshl_add_u64 v[208:209], s[22:23], 0, v[194:195]
	s_add_i32 m0, s49, 0x2000
	s_nop 0
	global_load_lds_dwordx4 v[208:209], off
	v_lshl_add_u64 v[208:209], s[28:29], 0, v[198:199]
	s_mov_b32 m0, s8
	s_nop 0
	global_load_lds_dwordx4 v[208:209], off
	s_mov_b32 m0, s9
	s_nop 0
	global_load_lds_dwordx4 v[210:211], off
	s_waitcnt vmcnt(8)
	s_waitcnt lgkmcnt(0)
	s_barrier
; #define PG8_STAGE(bufoff, gbase, voff) do { _Pragma("unroll") for (int _i = 0; _i < 2; ++_i) \
;         __builtin_amdgcn_global_load_lds((const unsigned*)((const char*)(gbase) + (voff)[_i]), (LAS unsigned*)(lds + (bufoff) + ldsw + _i * 8192), 16, 0, 0); } while (0)
; #define PG8_LDA(dst, b, h) do { _Pragma("unroll") for (int m = 0; m < 4; ++m) _Pragma("unroll") for (int k = 0; k < 2; ++k) dst[m][k] = *(const LAS bf16x8*)(lds + PG8_SA(b, h) + aoff + m * 2048 + k * 1024); } while (0)
; #define PG8_LDB(dst, b, h) do { _Pragma("unroll") for (int n = 0; n < 2; ++n) _Pragma("unroll") for (int k = 0; k < 2; ++k) dst[n][k] = *(const LAS bf16x8*)(lds + PG8_SB(b, h) + boff + n * 2048 + k * 1024); } while (0)
; #define PG8_MMA(ai, bj, At, Bt) do { __builtin_amdgcn_s_setprio(1); _Pragma("unroll") for (int m = 0; m < 4; ++m) _Pragma("unroll") for (int n = 0; n < 2; ++n) _Pragma("unroll") for (int k = 0; k < 2; ++k) \
;         acc[ai][bj][m][n] = __builtin_amdgcn_mfma_f32_16x16x32_bf16(Bt[n][k], At[m][k], acc[ai][bj][m][n], 0, 0, 0); __builtin_amdgcn_s_setprio(0); } while (0)
; #define PG8_WAIT_V(n) asm volatile("s_waitcnt vmcnt(" #n ")" ::: "memory")
; #define PG8_WAIT_L(n) asm volatile("s_waitcnt lgkmcnt(" #n ")" ::: "memory")
; #define PG8_BAR __builtin_amdgcn_s_barrier()
; #define PG8_SCHED __builtin_amdgcn_sched_barrier(0)
; template <class Epi, class Sched, bool ALIGN_EPI = false, bool SP2 = false>
; __device__ __forceinline__ void gemm_phase(LAS unsigned char* lds, const Gemm g, const Sched& S, const Epi& E) {
;     ...
;             PG8_WAIT_V(8); PG8_WAIT_L(0); PG8_BAR; PG8_MMA(1, 0, At, B0); PG8_MMA(1, 1, At, B1); PG8_BAR; PG8_SCHED;
;             PG8_LDB(B0, 1, 0); PG8_LDB(B1, 1, 1); PG8_SCHED; PG8_LDA(At, 1, 0); PG8_STAGE(PG8_SA(0, 1), a2 + hstep, voffA);
;             PG8_WAIT_V(8); PG8_WAIT_L(0); PG8_BAR; PG8_MMA(0, 0, At, B0); PG8_MMA(0, 1, At, B1); PG8_BAR; PG8_SCHED;
	v_mfma_f32_16x16x32_bf16 v[62:65], v[90:93], v[162:165], v[62:65]
	v_mfma_f32_16x16x32_bf16 v[62:65], v[102:105], v[166:169], v[62:65]
	v_mfma_f32_16x16x32_bf16 v[58:61], v[114:117], v[162:165], v[58:61]
	v_mfma_f32_16x16x32_bf16 v[58:61], v[126:129], v[166:169], v[58:61]
	v_mfma_f32_16x16x32_bf16 v[42:45], v[114:117], v[170:173], v[42:45]
	v_mfma_f32_16x16x32_bf16 v[42:45], v[126:129], v[174:177], v[42:45]
	v_mfma_f32_16x16x32_bf16 v[46:49], v[90:93], v[170:173], v[46:49]
	v_mfma_f32_16x16x32_bf16 v[46:49], v[102:105], v[174:177], v[46:49]
	v_mfma_f32_16x16x32_bf16 v[30:33], v[90:93], v[178:181], v[30:33]
	v_mfma_f32_16x16x32_bf16 v[30:33], v[102:105], v[182:185], v[30:33]
	v_mfma_f32_16x16x32_bf16 v[26:29], v[114:117], v[178:181], v[26:29]
	v_mfma_f32_16x16x32_bf16 v[26:29], v[126:129], v[182:185], v[26:29]
	v_mfma_f32_16x16x32_bf16 v[10:13], v[114:117], v[186:189], v[10:13]
	v_mfma_f32_16x16x32_bf16 v[10:13], v[126:129], v[190:193], v[10:13]
	v_mfma_f32_16x16x32_bf16 v[14:17], v[90:93], v[186:189], v[14:17]
	v_mfma_f32_16x16x32_bf16 v[14:17], v[102:105], v[190:193], v[14:17]
	v_mfma_f32_16x16x32_bf16 v[54:57], v[138:141], v[162:165], v[54:57]
	v_mfma_f32_16x16x32_bf16 v[54:57], v[142:145], v[166:169], v[54:57]
	v_mfma_f32_16x16x32_bf16 v[50:53], v[154:157], v[162:165], v[50:53]
	v_mfma_f32_16x16x32_bf16 v[50:53], v[158:161], v[166:169], v[50:53]
	v_mfma_f32_16x16x32_bf16 v[34:37], v[154:157], v[170:173], v[34:37]
	v_mfma_f32_16x16x32_bf16 v[34:37], v[158:161], v[174:177], v[34:37]
	v_mfma_f32_16x16x32_bf16 v[38:41], v[138:141], v[170:173], v[38:41]
	v_mfma_f32_16x16x32_bf16 v[38:41], v[142:145], v[174:177], v[38:41]
	v_mfma_f32_16x16x32_bf16 v[22:25], v[138:141], v[178:181], v[22:25]
	v_mfma_f32_16x16x32_bf16 v[22:25], v[142:145], v[182:185], v[22:25]
	v_mfma_f32_16x16x32_bf16 v[18:21], v[154:157], v[178:181], v[18:21]
	v_mfma_f32_16x16x32_bf16 v[18:21], v[158:161], v[182:185], v[18:21]
	v_mfma_f32_16x16x32_bf16 v[2:5], v[154:157], v[186:189], v[2:5]
	v_mfma_f32_16x16x32_bf16 v[2:5], v[158:161], v[190:193], v[2:5]
	v_mfma_f32_16x16x32_bf16 v[6:9], v[138:141], v[186:189], v[6:9]
	v_mfma_f32_16x16x32_bf16 v[6:9], v[142:145], v[190:193], v[6:9]
	s_barrier
	s_add_i32 s49, 0, 0x18000
	s_add_i32 s50, 0, 0x1c000
	v_add_u32_e32 v126, s49, v247
	v_add_u32_e32 v158, s50, v247
	ds_read_b128 v[90:93], v126
	ds_read_b128 v[102:105], v126 offset:1024
	ds_read_b128 v[114:117], v126 offset:2048
	ds_read_b128 v[126:129], v126 offset:3072
	ds_read_b128 v[138:141], v158
	ds_read_b128 v[142:145], v158 offset:1024
	ds_read_b128 v[154:157], v158 offset:2048
	ds_read_b128 v[158:161], v158 offset:3072
	s_add_u32 s22, s28, 0x160000
	s_addc_u32 s23, s29, 0
	s_mov_b32 m0, s30
	v_lshl_add_u64 v[212:213], s[22:23], 0, v[198:199]
	ds_read_b128 v[162:165], v249 offset:32768
	ds_read_b128 v[166:169], v249 offset:33792
	ds_read_b128 v[170:173], v249 offset:34816
	ds_read_b128 v[174:177], v249 offset:35840
	ds_read_b128 v[178:181], v249 offset:36864
	ds_read_b128 v[182:185], v249 offset:37888
	ds_read_b128 v[186:189], v249 offset:38912
	ds_read_b128 v[190:193], v249 offset:39936
	global_load_lds_dwordx4 v[212:213], off
	v_lshl_add_u64 v[212:213], s[22:23], 0, v[196:197]
	s_mov_b32 m0, s31
	s_nop 0
	global_load_lds_dwordx4 v[212:213], off
	s_waitcnt vmcnt(8)
	s_waitcnt lgkmcnt(0)
	s_barrier
	v_mfma_f32_16x16x32_bf16 v[150:153], v[90:93], v[162:165], v[150:153]
	v_mfma_f32_16x16x32_bf16 v[150:153], v[102:105], v[166:169], v[150:153]
	v_mfma_f32_16x16x32_bf16 v[146:149], v[114:117], v[162:165], v[146:149]
	v_mfma_f32_16x16x32_bf16 v[146:149], v[126:129], v[166:169], v[146:149]
	v_mfma_f32_16x16x32_bf16 v[118:121], v[114:117], v[170:173], v[118:121]
	v_mfma_f32_16x16x32_bf16 v[118:121], v[126:129], v[174:177], v[118:121]
	v_mfma_f32_16x16x32_bf16 v[122:125], v[90:93], v[170:173], v[122:125]
	v_mfma_f32_16x16x32_bf16 v[122:125], v[102:105], v[174:177], v[122:125]
	v_mfma_f32_16x16x32_bf16 v[98:101], v[90:93], v[178:181], v[98:101]
	v_mfma_f32_16x16x32_bf16 v[98:101], v[102:105], v[182:185], v[98:101]
	v_mfma_f32_16x16x32_bf16 v[94:97], v[114:117], v[178:181], v[94:97]
	v_mfma_f32_16x16x32_bf16 v[94:97], v[126:129], v[182:185], v[94:97]
	v_mfma_f32_16x16x32_bf16 v[74:77], v[114:117], v[186:189], v[74:77]
	v_mfma_f32_16x16x32_bf16 v[74:77], v[126:129], v[190:193], v[74:77]
	v_mfma_f32_16x16x32_bf16 v[78:81], v[90:93], v[186:189], v[78:81]
	v_mfma_f32_16x16x32_bf16 v[78:81], v[102:105], v[190:193], v[78:81]
	v_mfma_f32_16x16x32_bf16 v[134:137], v[138:141], v[162:165], v[134:137]
	v_mfma_f32_16x16x32_bf16 v[134:137], v[142:145], v[166:169], v[134:137]
	v_mfma_f32_16x16x32_bf16 v[130:133], v[154:157], v[162:165], v[130:133]
	v_mfma_f32_16x16x32_bf16 v[130:133], v[158:161], v[166:169], v[130:133]
	v_mfma_f32_16x16x32_bf16 v[106:109], v[154:157], v[170:173], v[106:109]
	v_mfma_f32_16x16x32_bf16 v[106:109], v[158:161], v[174:177], v[106:109]
	v_mfma_f32_16x16x32_bf16 v[110:113], v[138:141], v[170:173], v[110:113]
	v_mfma_f32_16x16x32_bf16 v[110:113], v[142:145], v[174:177], v[110:113]
	v_mfma_f32_16x16x32_bf16 v[86:89], v[138:141], v[178:181], v[86:89]
	v_mfma_f32_16x16x32_bf16 v[86:89], v[142:145], v[182:185], v[86:89]
	v_mfma_f32_16x16x32_bf16 v[82:85], v[154:157], v[178:181], v[82:85]
	v_mfma_f32_16x16x32_bf16 v[82:85], v[158:161], v[182:185], v[82:85]
	v_mfma_f32_16x16x32_bf16 v[66:69], v[154:157], v[186:189], v[66:69]
	v_mfma_f32_16x16x32_bf16 v[66:69], v[158:161], v[190:193], v[66:69]
	v_mfma_f32_16x16x32_bf16 v[70:73], v[138:141], v[186:189], v[70:73]
	v_mfma_f32_16x16x32_bf16 v[70:73], v[142:145], v[190:193], v[70:73]
	s_barrier
; #define PG8_STAGE(bufoff, gbase, voff) do { _Pragma("unroll") for (int _i = 0; _i < 2; ++_i) \
;         __builtin_amdgcn_global_load_lds((const unsigned*)((const char*)(gbase) + (voff)[_i]), (LAS unsigned*)(lds + (bufoff) + ldsw + _i * 8192), 16, 0, 0); } while (0)
; #define PG8_LDA(dst, b, h) do { _Pragma("unroll") for (int m = 0; m < 4; ++m) _Pragma("unroll") for (int k = 0; k < 2; ++k) dst[m][k] = *(const LAS bf16x8*)(lds + PG8_SA(b, h) + aoff + m * 2048 + k * 1024); } while (0)
; #define PG8_MMA(ai, bj, At, Bt) do { __builtin_amdgcn_s_setprio(1); _Pragma("unroll") for (int m = 0; m < 4; ++m) _Pragma("unroll") for (int n = 0; n < 2; ++n) _Pragma("unroll") for (int k = 0; k < 2; ++k) \
;         acc[ai][bj][m][n] = __builtin_amdgcn_mfma_f32_16x16x32_bf16(Bt[n][k], At[m][k], acc[ai][bj][m][n], 0, 0, 0); __builtin_amdgcn_s_setprio(0); } while (0)
; #define PG8_WAIT_V(n) asm volatile("s_waitcnt vmcnt(" #n ")" ::: "memory")
; #define PG8_WAIT_L(n) asm volatile("s_waitcnt lgkmcnt(" #n ")" ::: "memory")
; #define PG8_BAR __builtin_amdgcn_s_barrier()
; #define PG8_SCHED __builtin_amdgcn_sched_barrier(0)
; template <class Epi, class Sched, bool ALIGN_EPI = false, bool SP2 = false>
; __device__ __forceinline__ void gemm_phase(LAS unsigned char* lds, const Gemm g, const Sched& S, const Epi& E) {
;     ...
;             PG8_LDA(At, 1, 1); PG8_STAGE(PG8_SB(1, 0), b3, voffB); PG8_STAGE(PG8_SB(1, 1), b3 + hstep, voffB); PG8_STAGE(PG8_SA(1, 0), a3, voffA);
;             PG8_WAIT_V(8); PG8_WAIT_L(0); PG8_BAR; PG8_MMA(1, 0, At, B0); PG8_MMA(1, 1, At, B1); PG8_BAR; PG8_SCHED;
;     ...
;         if constexpr (ALIGN_EPI) { if (wr == 0) PG8_BAR; }
	s_add_i32 s22, s49, s7
	v_lshl_add_u64 v[204:205], v[204:205], 0, s[12:13]
	s_mov_b32 m0, s22
	ds_read_b128 v[162:165], v249 offset:49152
	ds_read_b128 v[166:169], v249 offset:50176
	ds_read_b128 v[170:173], v249 offset:51200
	ds_read_b128 v[174:177], v249 offset:52224
	ds_read_b128 v[178:181], v249 offset:53248
	ds_read_b128 v[182:185], v249 offset:54272
	ds_read_b128 v[186:189], v249 offset:55296
	ds_read_b128 v[190:193], v249 offset:56320
	global_load_lds_dwordx4 v[204:205], off
	s_add_i32 m0, s22, 0x2000
	s_add_u32 s22, s26, 0x160080
	v_lshl_add_u64 v[204:205], v[206:207], 0, s[12:13]
	s_addc_u32 s23, s27, 0
	s_add_i32 s26, s50, s7
	global_load_lds_dwordx4 v[204:205], off
	v_lshl_add_u64 v[204:205], s[22:23], 0, v[0:1]
	s_mov_b32 m0, s26
	s_nop 0
	global_load_lds_dwordx4 v[204:205], off
	v_lshl_add_u64 v[204:205], s[22:23], 0, v[194:195]
	s_add_i32 m0, s26, 0x2000
	s_nop 0
	global_load_lds_dwordx4 v[204:205], off
	v_lshl_add_u64 v[204:205], v[208:209], 0, s[12:13]
	s_mov_b32 m0, s35
	s_nop 0
	global_load_lds_dwordx4 v[204:205], off
	v_lshl_add_u64 v[204:205], v[210:211], 0, s[12:13]
	s_mov_b32 m0, s40
	s_nop 0
	global_load_lds_dwordx4 v[204:205], off
	s_waitcnt vmcnt(8)
	s_waitcnt lgkmcnt(0)
	s_barrier
	v_mfma_f32_16x16x32_bf16 v[62:65], v[90:93], v[162:165], v[62:65]
	v_mfma_f32_16x16x32_bf16 v[62:65], v[102:105], v[166:169], v[62:65]
	v_mfma_f32_16x16x32_bf16 v[58:61], v[114:117], v[162:165], v[58:61]
	v_mfma_f32_16x16x32_bf16 v[58:61], v[126:129], v[166:169], v[58:61]
	v_mfma_f32_16x16x32_bf16 v[42:45], v[114:117], v[170:173], v[42:45]
	v_mfma_f32_16x16x32_bf16 v[42:45], v[126:129], v[174:177], v[42:45]
	v_mfma_f32_16x16x32_bf16 v[46:49], v[90:93], v[170:173], v[46:49]
	v_mfma_f32_16x16x32_bf16 v[46:49], v[102:105], v[174:177], v[46:49]
	v_mfma_f32_16x16x32_bf16 v[30:33], v[90:93], v[178:181], v[30:33]
	v_mfma_f32_16x16x32_bf16 v[30:33], v[102:105], v[182:185], v[30:33]
	v_mfma_f32_16x16x32_bf16 v[26:29], v[114:117], v[178:181], v[26:29]
	v_mfma_f32_16x16x32_bf16 v[26:29], v[126:129], v[182:185], v[26:29]
	v_mfma_f32_16x16x32_bf16 v[10:13], v[114:117], v[186:189], v[10:13]
	v_mfma_f32_16x16x32_bf16 v[10:13], v[126:129], v[190:193], v[10:13]
	v_mfma_f32_16x16x32_bf16 v[14:17], v[90:93], v[186:189], v[14:17]
	v_mfma_f32_16x16x32_bf16 v[14:17], v[102:105], v[190:193], v[14:17]
	v_mfma_f32_16x16x32_bf16 v[54:57], v[138:141], v[162:165], v[54:57]
	v_mfma_f32_16x16x32_bf16 v[54:57], v[142:145], v[166:169], v[54:57]
	v_mfma_f32_16x16x32_bf16 v[50:53], v[154:157], v[162:165], v[50:53]
	v_mfma_f32_16x16x32_bf16 v[50:53], v[158:161], v[166:169], v[50:53]
	v_mfma_f32_16x16x32_bf16 v[34:37], v[154:157], v[170:173], v[34:37]
	v_mfma_f32_16x16x32_bf16 v[34:37], v[158:161], v[174:177], v[34:37]
	v_mfma_f32_16x16x32_bf16 v[38:41], v[138:141], v[170:173], v[38:41]
	v_mfma_f32_16x16x32_bf16 v[38:41], v[142:145], v[174:177], v[38:41]
	v_mfma_f32_16x16x32_bf16 v[22:25], v[138:141], v[178:181], v[22:25]
	v_mfma_f32_16x16x32_bf16 v[22:25], v[142:145], v[182:185], v[22:25]
	v_mfma_f32_16x16x32_bf16 v[18:21], v[154:157], v[178:181], v[18:21]
	v_mfma_f32_16x16x32_bf16 v[18:21], v[158:161], v[182:185], v[18:21]
	v_mfma_f32_16x16x32_bf16 v[2:5], v[154:157], v[186:189], v[2:5]
	v_mfma_f32_16x16x32_bf16 v[2:5], v[158:161], v[190:193], v[2:5]
	v_mfma_f32_16x16x32_bf16 v[6:9], v[138:141], v[186:189], v[6:9]
	v_mfma_f32_16x16x32_bf16 v[6:9], v[142:145], v[190:193], v[6:9]
	s_barrier
	s_add_i32 s48, s48, 2
	s_add_u32 s46, s46, 0x100
	s_addc_u32 s47, s47, 0
	s_cmpk_gt_u32 s48, 0x55
	s_mov_b64 s[22:23], s[24:25]
	s_cbranch_scc0 .LBB0_1007
	s_and_b64 vcc, exec, s[18:19]
	s_cbranch_vccz .LBB0_1010
	s_barrier
